# phase-start de-serialisation: SGU parameter loads waited for behind the unit's loads; attention set-up's bias-table values fetched at the start of the phase
# speedup vs baseline: 1.0002x; 1.0002x over previous
.LBB0_419:
	s_or_b64 exec, exec, s[0:1]
	v_mov_b32_e32 v96, v217
	s_waitcnt lgkmcnt(0)
	s_barrier
	s_mov_b32 s1, 0
	v_ashrrev_i32_e32 v97, 31, v96
	v_lshlrev_b64 v[0:1], 2, v[96:97]
	v_lshl_add_u64 v[2:3], s[16:17], 0, v[0:1]
	v_lshl_add_u64 v[0:1], s[20:21], 0, v[0:1]
	global_load_dword v192, v[2:3], off
	v_readfirstlane_b32 s9, v96
	global_load_dword v193, v[0:1], off
	s_ashr_i32 s8, s9, 6
	v_mbcnt_lo_u32_b32 v154, -1, 0
	v_and_b32_e32 v226, 63, v96
	v_lshl_add_u32 v1, v96, 2, 0
	v_lshl_add_u32 v194, v96, 2, 0
	v_and_b32_e32 v150, 15, v96
	v_and_b32_e32 v151, 3, v96
	v_lshrrev_b32_e32 v152, 1, v96
	s_cmpk_gt_i32 s2, 0xff
	v_and_b32_e32 v153, 48, v96
	s_cbranch_scc1 .LBB0_422
	v_mbcnt_hi_u32_b32 v2, -1, v154
	v_and_b32_e32 v4, 64, v2
	v_xor_b32_e32 v3, 1, v2
	v_add_u32_e32 v4, 64, v4
	v_cmp_lt_i32_e32 vcc, v3, v4
	s_lshl_b32 s0, s8, 4
	s_ashr_i32 s4, s0, 31
	v_cndmask_b32_e32 v3, v2, v3, vcc
	v_lshlrev_b32_e32 v155, 2, v3
	v_xor_b32_e32 v3, 2, v2
	v_or_b32_e32 v100, s0, v150
	v_cmp_lt_i32_e32 vcc, v3, v4
	s_movk_i32 s0, 0x110
	v_and_b32_e32 v0, 24, v152
	v_cndmask_b32_e32 v2, v2, v3, vcc
	v_mul_lo_u32 v3, v100, s0
	v_add_u32_e32 v21, 0, v3
	v_bfe_u32 v3, v96, 2, 2
	v_or_b32_e32 v3, v0, v3
	v_lshlrev_b32_e32 v4, 4, v226
	v_mov_b32_e32 v101, s4
	s_add_i32 s4, 0, 0x10800
	v_mul_u32_u24_e32 v3, 0x110, v3
	v_and_b32_e32 v4, 48, v4
	v_add3_u32 v159, s4, v3, v4
	v_add_u32_e32 v3, 0x200, v96
	v_ashrrev_i32_e32 v8, 4, v3
	v_add_u32_e32 v3, 0x400, v96
	v_ashrrev_i32_e32 v12, 4, v3
	v_add_u32_e32 v3, 0x600, v96
	v_lshlrev_b32_e32 v1, 4, v96
	v_ashrrev_i32_e32 v4, 4, v96
	v_ashrrev_i32_e32 v16, 4, v3
	v_ashrrev_i32_e32 v98, 2, v96
	v_and_b32_e32 v102, 0xf0, v1
	s_lshl_b32 s5, s8, 6
	v_mov_b32_e32 v103, 0
	v_ashrrev_i32_e32 v5, 31, v4
	v_ashrrev_i32_e32 v9, 31, v8
	v_ashrrev_i32_e32 v13, 31, v12
	v_ashrrev_i32_e32 v17, 31, v16
	v_lshlrev_b32_e32 v156, 2, v2
	v_mul_lo_u32 v2, v98, s0
	s_add_i32 s5, s5, 0
	v_lshlrev_b64 v[6:7], 8, v[4:5]
	v_lshlrev_b64 v[10:11], 8, v[8:9]
	v_lshlrev_b64 v[14:15], 8, v[12:13]
	v_lshlrev_b64 v[18:19], 8, v[16:17]
	v_mul_lo_u32 v9, v4, s0
	v_lshl_add_u64 v[4:5], s[46:47], 0, v[102:103]
	v_add_u32_e32 v20, s4, v2
	v_lshl_add_u32 v158, v150, 2, s5
	v_lshl_add_u64 v[104:105], v[4:5], 0, v[6:7]
	v_lshl_add_u64 v[106:107], v[4:5], 0, v[10:11]
	v_lshl_add_u64 v[108:109], v[4:5], 0, v[14:15]
	v_lshl_add_u64 v[110:111], v[4:5], 0, v[18:19]
	s_mov_b64 s[4:5], 0x8000
	v_lshl_add_u64 v[112:113], v[104:105], 0, s[4:5]
	v_lshl_add_u64 v[114:115], v[106:107], 0, s[4:5]
	v_lshl_add_u64 v[116:117], v[108:109], 0, s[4:5]
	v_lshl_add_u64 v[118:119], v[110:111], 0, s[4:5]
	s_mov_b64 s[4:5], 0x10000
	v_readlane_b32 s12, v252, 0
	v_add_u32_e32 v1, 0, v102
	v_lshlrev_b32_e32 v2, 6, v151
	v_mul_lo_u32 v8, v8, s0
	v_mul_lo_u32 v12, v12, s0
	v_mul_lo_u32 v13, v16, s0
	v_lshl_add_u64 v[120:121], v[104:105], 0, s[4:5]
	v_lshl_add_u64 v[122:123], v[106:107], 0, s[4:5]
	v_lshl_add_u64 v[124:125], v[108:109], 0, s[4:5]
	v_lshl_add_u64 v[126:127], v[110:111], 0, s[4:5]
	s_mov_b64 s[4:5], 0x18000
	v_mov_b32_e32 v3, v103
	v_lshlrev_b32_e32 v102, 1, v0
	v_readlane_b32 s13, v252, 1
	v_ashrrev_i32_e32 v99, 31, v98
	v_lshl_add_u32 v157, v151, 7, 0
	v_lshl_add_u64 v[128:129], v[104:105], 0, s[4:5]
	v_lshl_add_u64 v[130:131], v[106:107], 0, s[4:5]
	v_lshl_add_u64 v[132:133], v[108:109], 0, s[4:5]
	v_lshl_add_u64 v[134:135], v[110:111], 0, s[4:5]
	v_lshl_add_u64 v[136:137], s[50:51], 0, v[2:3]
	v_lshl_add_u64 v[138:139], s[48:49], 0, v[102:103]
	v_lshl_add_u64 v[140:141], s[12:13], 0, v[102:103]
	s_lshl_b32 s10, s2, 7
	s_lshl_b32 s11, s3, 7
	v_add_u32_e32 v160, v1, v9
	v_add_u32_e32 v161, v1, v8
	v_add_u32_e32 v162, v1, v12
	v_add_u32_e32 v163, v1, v13
	v_mov_b32_e32 v164, 0x358637bd
	v_add_u32_e32 v165, v20, v2
	v_add_u32_e32 v166, v21, v153
	v_lshlrev_b32_e32 v102, 1, v0
	s_mov_b32 s12, s2
	v_readlane_b32 s14, v252, 2
	v_readlane_b32 s15, v252, 3
	v_readlane_b32 s16, v252, 4
	v_readlane_b32 s17, v252, 5
	v_readlane_b32 s18, v252, 6
	v_readlane_b32 s19, v252, 7
.LBB0_421:
	s_ashr_i32 s6, s12, 5
	s_ashr_i32 s7, s6, 31
	s_mul_i32 s4, s6, 0x1100
	s_and_b32 s0, s10, 0xf80
	s_mul_hi_i32 s5, s6, 0x1100
	s_add_u32 s4, s4, s0
	s_addc_u32 s5, s5, 0
	v_lshl_add_u64 v[0:1], s[4:5], 0, v[98:99]
	v_lshlrev_b64 v[0:1], 10, v[0:1]
	v_lshl_add_u64 v[142:143], v[136:137], 0, v[0:1]
	global_load_dwordx4 v[0:3], v[104:105], off
	global_load_dwordx4 v[4:7], v[142:143], off offset:48
	global_load_dwordx4 v[8:11], v[142:143], off offset:32
	global_load_dwordx4 v[12:15], v[142:143], off offset:16
	global_load_dwordx4 v[16:19], v[142:143], off
	global_load_dwordx4 v[20:23], v[106:107], off
	global_load_dwordx4 v[24:27], v[108:109], off
	global_load_dwordx4 v[28:31], v[110:111], off
	v_lshl_add_u64 v[32:33], s[4:5], 0, v[100:101]
	v_lshlrev_b64 v[32:33], 10, v[32:33]
	v_lshl_add_u64 v[144:145], v[138:139], 0, v[32:33]
	v_lshl_add_u64 v[146:147], v[140:141], 0, v[32:33]
	global_load_dwordx4 v[92:95], v[144:145], off
	global_load_dwordx4 v[64:67], v[146:147], off
	global_load_dwordx4 v[88:91], v[144:145], off offset:64
	global_load_dwordx4 v[68:71], v[146:147], off offset:64
	global_load_dwordx4 v[84:87], v[144:145], off offset:128
	global_load_dwordx4 v[72:75], v[146:147], off offset:128
	global_load_dwordx4 v[80:83], v[144:145], off offset:192
	global_load_dwordx4 v[76:79], v[146:147], off offset:192
	s_waitcnt vmcnt(16)
	ds_write2st64_b32 v194, v192, v193 offset1:8
	s_waitcnt lgkmcnt(0)
	s_barrier
	v_lshl_add_u64 v[32:33], v[100:101], 0, s[0:1]
	v_lshlrev_b64 v[148:149], 11, v[32:33]
	s_lshl_b64 s[6:7], s[6:7], 23
	s_add_u32 s4, s78, s6
	s_addc_u32 s5, s79, s7
	s_add_i32 s12, s12, s3
	s_add_i32 s10, s10, s11
	s_cmpk_lt_i32 s12, 0x100
	s_waitcnt vmcnt(15)
	ds_write_b128 v160, v[0:3] offset:32768
	s_waitcnt vmcnt(10)
	ds_write_b128 v161, v[20:23] offset:32768
	s_waitcnt vmcnt(9)
	ds_write_b128 v162, v[24:27] offset:32768
	s_waitcnt vmcnt(8)
	ds_write_b128 v163, v[28:31] offset:32768
	v_lshlrev_b32_e32 v20, 16, v16
	v_and_b32_e32 v16, 0xffff0000, v16
	v_lshlrev_b32_e32 v21, 16, v17
	v_and_b32_e32 v17, 0xffff0000, v17
	v_mul_f32_e32 v0, v16, v16
	v_mul_f32_e32 v1, v17, v17
	v_fmac_f32_e32 v0, v20, v20
	v_fmac_f32_e32 v1, v21, v21
	v_lshlrev_b32_e32 v22, 16, v18
	v_and_b32_e32 v18, 0xffff0000, v18
	v_add_f32_e32 v0, v0, v1
	v_mul_f32_e32 v1, v18, v18
	v_fmac_f32_e32 v1, v22, v22
	v_lshlrev_b32_e32 v23, 16, v19
	v_and_b32_e32 v19, 0xffff0000, v19
	v_add_f32_e32 v0, v1, v0
	v_mul_f32_e32 v1, v19, v19
	v_fmac_f32_e32 v1, v23, v23
	v_and_b32_e32 v25, 0xffff0000, v12
	v_add_f32_e32 v0, v1, v0
	v_lshlrev_b32_e32 v24, 16, v12
	v_mul_f32_e32 v1, v25, v25
	v_fmac_f32_e32 v1, v24, v24
	v_and_b32_e32 v27, 0xffff0000, v13
	v_add_f32_e32 v0, v1, v0
	v_lshlrev_b32_e32 v26, 16, v13
	v_mul_f32_e32 v1, v27, v27
	v_fmac_f32_e32 v1, v26, v26
	v_and_b32_e32 v29, 0xffff0000, v14
	v_add_f32_e32 v0, v1, v0
	v_lshlrev_b32_e32 v28, 16, v14
	v_mul_f32_e32 v1, v29, v29
	v_fmac_f32_e32 v1, v28, v28
	v_and_b32_e32 v31, 0xffff0000, v15
	v_add_f32_e32 v0, v1, v0
	v_lshlrev_b32_e32 v30, 16, v15
	v_mul_f32_e32 v1, v31, v31
	v_fmac_f32_e32 v1, v30, v30
	v_and_b32_e32 v33, 0xffff0000, v8
	v_add_f32_e32 v0, v1, v0
	v_lshlrev_b32_e32 v32, 16, v8
	v_mul_f32_e32 v1, v33, v33
	v_fmac_f32_e32 v1, v32, v32
	v_and_b32_e32 v35, 0xffff0000, v9
	v_add_f32_e32 v0, v1, v0
	v_lshlrev_b32_e32 v34, 16, v9
	v_mul_f32_e32 v1, v35, v35
	v_fmac_f32_e32 v1, v34, v34
	v_and_b32_e32 v37, 0xffff0000, v10
	v_add_f32_e32 v0, v1, v0
	v_lshlrev_b32_e32 v36, 16, v10
	v_mul_f32_e32 v1, v37, v37
	v_fmac_f32_e32 v1, v36, v36
	v_and_b32_e32 v39, 0xffff0000, v11
	v_add_f32_e32 v0, v1, v0
	v_lshlrev_b32_e32 v38, 16, v11
	v_mul_f32_e32 v1, v39, v39
	v_fmac_f32_e32 v1, v38, v38
	v_and_b32_e32 v11, 0xffff0000, v5
	v_and_b32_e32 v10, 0xffff0000, v4
	v_add_f32_e32 v2, v1, v0
	v_lshlrev_b32_e32 v9, 16, v5
	v_lshlrev_b32_e32 v8, 16, v4
	v_pk_mul_f32 v[0:1], v[10:11], v[10:11]
	v_and_b32_e32 v15, 0xffff0000, v7
	v_pk_fma_f32 v[0:1], v[8:9], v[8:9], v[0:1]
	v_and_b32_e32 v14, 0xffff0000, v6
	v_add_f32_e32 v0, v0, v2
	v_add_f32_e32 v2, v1, v0
	v_lshlrev_b32_e32 v13, 16, v7
	v_lshlrev_b32_e32 v12, 16, v6
	v_pk_mul_f32 v[0:1], v[14:15], v[14:15]
	s_nop 0
	v_pk_fma_f32 v[0:1], v[12:13], v[12:13], v[0:1]
	s_nop 0
	v_add_f32_e32 v0, v0, v2
	v_add_f32_e32 v0, v1, v0
	ds_bpermute_b32 v1, v155, v0
	s_waitcnt lgkmcnt(0)
	v_add_f32_e32 v0, v0, v1
	ds_bpermute_b32 v1, v156, v0
	s_waitcnt lgkmcnt(0)
	v_add_f32_e32 v0, v0, v1
	v_fmamk_f32 v0, v0, 0x3c000000, v164
	v_rsq_f32_e32 v40, v0
	ds_read_b128 v[0:3], v157
	ds_read_b128 v[4:7], v157 offset:16
	v_mul_f32_e32 v20, v40, v20
	v_mul_f32_e32 v16, v40, v16
	s_waitcnt lgkmcnt(1)
	v_mul_f32_e32 v0, v0, v20
	v_mul_f32_e32 v1, v1, v16
	v_cvt_pk_bf16_f32 v0, v0, v1
	v_mul_f32_e32 v1, v40, v21
	v_mul_f32_e32 v1, v2, v1
	v_mul_f32_e32 v2, v40, v17
	v_mul_f32_e32 v2, v3, v2
	v_cvt_pk_bf16_f32 v1, v1, v2
	v_mul_f32_e32 v2, v40, v22
	v_mul_f32_e32 v3, v40, v18
	s_waitcnt lgkmcnt(0)
	v_mul_f32_e32 v2, v4, v2
	v_mul_f32_e32 v3, v5, v3
	v_cvt_pk_bf16_f32 v2, v2, v3
	v_mul_f32_e32 v3, v40, v23
	v_mul_f32_e32 v3, v6, v3
	v_mul_f32_e32 v4, v40, v19
	v_mul_f32_e32 v4, v7, v4
	v_cvt_pk_bf16_f32 v3, v3, v4
	ds_write_b128 v165, v[0:3]
	ds_read_b128 v[0:3], v157 offset:32
	ds_read_b128 v[4:7], v157 offset:48
	v_mul_f32_e32 v16, v40, v24
	v_mul_f32_e32 v8, v40, v8
	s_waitcnt lgkmcnt(1)
	v_mul_f32_e32 v0, v16, v0
	v_mul_f32_e32 v16, v40, v25
	v_mul_f32_e32 v1, v16, v1
	v_cvt_pk_bf16_f32 v0, v0, v1
	v_mul_f32_e32 v1, v40, v26
	v_mul_f32_e32 v1, v1, v2
	v_mul_f32_e32 v2, v40, v27
	v_mul_f32_e32 v2, v2, v3
	v_cvt_pk_bf16_f32 v1, v1, v2
	v_mul_f32_e32 v2, v40, v28
	v_mul_f32_e32 v3, v40, v29
	s_waitcnt lgkmcnt(0)
	v_mul_f32_e32 v2, v2, v4
	v_mul_f32_e32 v3, v3, v5
	v_cvt_pk_bf16_f32 v2, v2, v3
	v_mul_f32_e32 v3, v40, v30
	v_mul_f32_e32 v3, v3, v6
	v_mul_f32_e32 v4, v40, v31
	v_mul_f32_e32 v4, v4, v7
	v_cvt_pk_bf16_f32 v3, v3, v4
	ds_write_b128 v165, v[0:3] offset:16
	ds_read_b128 v[0:3], v157 offset:64
	ds_read_b128 v[4:7], v157 offset:80
	v_mul_f32_e32 v16, v40, v32
	s_waitcnt lgkmcnt(1)
	v_mul_f32_e32 v0, v16, v0
	v_mul_f32_e32 v16, v40, v33
	v_mul_f32_e32 v1, v16, v1
	v_cvt_pk_bf16_f32 v0, v0, v1
	v_mul_f32_e32 v1, v40, v34
	v_mul_f32_e32 v1, v1, v2
	v_mul_f32_e32 v2, v40, v35
	v_mul_f32_e32 v2, v2, v3
	v_cvt_pk_bf16_f32 v1, v1, v2
	v_mul_f32_e32 v2, v40, v36
	v_mul_f32_e32 v3, v40, v37
	s_waitcnt lgkmcnt(0)
	v_mul_f32_e32 v2, v2, v4
	v_mul_f32_e32 v3, v3, v5
	v_cvt_pk_bf16_f32 v2, v2, v3
	v_mul_f32_e32 v3, v40, v38
	v_mul_f32_e32 v3, v3, v6
	v_mul_f32_e32 v4, v40, v39
	v_mul_f32_e32 v4, v4, v7
	v_cvt_pk_bf16_f32 v3, v3, v4
	ds_write_b128 v165, v[0:3] offset:32
	ds_read_b128 v[0:3], v157 offset:96
	ds_read_b128 v[4:7], v157 offset:112
	s_waitcnt lgkmcnt(1)
	v_mul_f32_e32 v0, v8, v0
	v_mul_f32_e32 v8, v40, v10
	v_mul_f32_e32 v1, v8, v1
	v_cvt_pk_bf16_f32 v0, v0, v1
	v_mul_f32_e32 v1, v40, v9
	v_mul_f32_e32 v1, v1, v2
	v_mul_f32_e32 v2, v40, v11
	v_mul_f32_e32 v2, v2, v3
	v_cvt_pk_bf16_f32 v1, v1, v2
	v_mul_f32_e32 v2, v40, v12
	v_mul_f32_e32 v3, v40, v14
	s_waitcnt lgkmcnt(0)
	v_mul_f32_e32 v2, v2, v4
	v_mul_f32_e32 v3, v3, v5
	v_cvt_pk_bf16_f32 v2, v2, v3
	v_mul_f32_e32 v3, v40, v13
	v_mul_f32_e32 v3, v3, v6
	v_mul_f32_e32 v4, v40, v15
	v_mul_f32_e32 v4, v4, v7
	v_cvt_pk_bf16_f32 v3, v3, v4
	ds_write_b128 v165, v[0:3] offset:48
	s_waitcnt lgkmcnt(0)
	s_barrier
	global_load_dwordx4 v[48:51], v[112:113], off
	global_load_dwordx4 v[32:35], v[142:143], off offset:304
	global_load_dwordx4 v[36:39], v[142:143], off offset:288
	global_load_dwordx4 v[40:43], v[142:143], off offset:272
	global_load_dwordx4 v[44:47], v[142:143], off offset:256
	global_load_dwordx4 v[52:55], v[114:115], off
	global_load_dwordx4 v[56:59], v[116:117], off
	global_load_dwordx4 v[60:63], v[118:119], off
	global_load_dwordx4 v[28:31], v[144:145], off offset:256
	global_load_dwordx4 v[24:27], v[146:147], off offset:256
	global_load_dwordx4 v[20:23], v[144:145], off offset:320
	global_load_dwordx4 v[16:19], v[146:147], off offset:320
	global_load_dwordx4 v[12:15], v[144:145], off offset:384
	global_load_dwordx4 v[8:11], v[146:147], off offset:384
	global_load_dwordx4 v[4:7], v[144:145], off offset:448
	global_load_dwordx4 v[0:3], v[146:147], off offset:448
	ds_read_b128 v[168:171], v166 offset:32768
	ds_read_b128 v[172:175], v166 offset:32832
	ds_read_b128 v[176:179], v166 offset:32896
	ds_read_b128 v[180:183], v166 offset:32960
	ds_read_b32 v167, v158 offset:2048
	ds_read_b64_tr_b16 v[184:185], v159
	ds_read_b64_tr_b16 v[186:187], v159 offset:1088
	ds_read_b64_tr_b16 v[188:189], v159 offset:8704
	ds_read_b64_tr_b16 v[190:191], v159 offset:9792
	s_waitcnt lgkmcnt(2)
	v_mfma_f32_16x16x32_bf16 v[184:187], v[184:187], v[168:171], 0
	s_waitcnt lgkmcnt(0)
	v_mfma_f32_16x16x32_bf16 v[184:187], v[188:191], v[172:175], v[184:187]
	ds_read_b64_tr_b16 v[188:189], v159 offset:17408
	ds_read_b64_tr_b16 v[190:191], v159 offset:18496
	s_waitcnt lgkmcnt(0)
	v_mfma_f32_16x16x32_bf16 v[184:187], v[188:191], v[176:179], v[184:187]
	ds_read_b64_tr_b16 v[188:189], v159 offset:26112
	ds_read_b64_tr_b16 v[190:191], v159 offset:27200
	s_waitcnt lgkmcnt(0)
	v_mfma_f32_16x16x32_bf16 v[184:187], v[188:191], v[180:183], v[184:187]
	s_waitcnt vmcnt(23)
	v_lshlrev_b32_e32 v188, 16, v92
	v_and_b32_e32 v92, 0xffff0000, v92
	s_nop 4
	v_add_f32_e32 v184, v167, v184
	v_add_f32_e32 v185, v167, v185
	v_mul_f32_e32 v184, v184, v188
	s_waitcnt vmcnt(22)
	v_lshlrev_b32_e32 v188, 16, v64
	v_mul_f32_e32 v92, v185, v92
	v_and_b32_e32 v64, 0xffff0000, v64
	v_mul_f32_e32 v64, v92, v64
	v_lshlrev_b32_e32 v92, 16, v93
	v_add_f32_e32 v185, v167, v186
	v_mul_f32_e32 v92, v185, v92
	v_lshlrev_b32_e32 v185, 16, v65
	v_mul_f32_e32 v92, v92, v185
	v_and_b32_e32 v93, 0xffff0000, v93
	v_add_f32_e32 v185, v167, v187
	v_mul_f32_e32 v93, v185, v93
	v_and_b32_e32 v65, 0xffff0000, v65
	v_mul_f32_e32 v184, v184, v188
	v_mul_f32_e32 v65, v93, v65
	v_cvt_pk_bf16_f32 v64, v184, v64
	v_cvt_pk_bf16_f32 v65, v92, v65
	ds_read_b64_tr_b16 v[184:185], v159 offset:8
	ds_read_b64_tr_b16 v[186:187], v159 offset:1096
	ds_read_b64_tr_b16 v[188:189], v159 offset:8712
	ds_read_b64_tr_b16 v[190:191], v159 offset:9800
	s_waitcnt lgkmcnt(2)
	v_mfma_f32_16x16x32_bf16 v[184:187], v[184:187], v[168:171], 0
	v_lshlrev_b32_e32 v92, 16, v94
	s_waitcnt lgkmcnt(0)
	v_mfma_f32_16x16x32_bf16 v[184:187], v[188:191], v[172:175], v[184:187]
	ds_read_b64_tr_b16 v[188:189], v159 offset:17416
	ds_read_b64_tr_b16 v[190:191], v159 offset:18504
	s_waitcnt lgkmcnt(0)
	v_mfma_f32_16x16x32_bf16 v[184:187], v[188:191], v[176:179], v[184:187]
	ds_read_b64_tr_b16 v[188:189], v159 offset:26120
	ds_read_b64_tr_b16 v[190:191], v159 offset:27208
	s_waitcnt lgkmcnt(0)
	v_mfma_f32_16x16x32_bf16 v[184:187], v[188:191], v[180:183], v[184:187]
	s_nop 7
	v_add_f32_e32 v93, v167, v184
	v_mul_f32_e32 v92, v93, v92
	v_lshlrev_b32_e32 v93, 16, v66
	v_mul_f32_e32 v92, v92, v93
	v_and_b32_e32 v93, 0xffff0000, v94
	v_add_f32_e32 v94, v167, v185
	v_mul_f32_e32 v93, v94, v93
	v_and_b32_e32 v66, 0xffff0000, v66
	v_mul_f32_e32 v66, v93, v66
	v_lshlrev_b32_e32 v93, 16, v95
	v_add_f32_e32 v94, v167, v186
	v_mul_f32_e32 v93, v94, v93
	v_lshlrev_b32_e32 v94, 16, v67
	v_mul_f32_e32 v93, v93, v94
	v_and_b32_e32 v94, 0xffff0000, v95
	v_add_f32_e32 v95, v167, v187
	v_mul_f32_e32 v94, v95, v94
	v_and_b32_e32 v67, 0xffff0000, v67
	v_mul_f32_e32 v67, v94, v67
	v_cvt_pk_bf16_f32 v66, v92, v66
	v_cvt_pk_bf16_f32 v67, v93, v67
	ds_read_b64_tr_b16 v[92:93], v159 offset:64
	ds_read_b64_tr_b16 v[94:95], v159 offset:1152
	ds_read_b64_tr_b16 v[184:185], v159 offset:8768
	ds_read_b64_tr_b16 v[186:187], v159 offset:9856
	s_waitcnt lgkmcnt(2)
	v_mfma_f32_16x16x32_bf16 v[92:95], v[92:95], v[168:171], 0
	s_waitcnt lgkmcnt(0)
	v_mfma_f32_16x16x32_bf16 v[92:95], v[184:187], v[172:175], v[92:95]
	ds_read_b64_tr_b16 v[184:185], v159 offset:17472
	ds_read_b64_tr_b16 v[186:187], v159 offset:18560
	s_waitcnt lgkmcnt(0)
	v_mfma_f32_16x16x32_bf16 v[92:95], v[184:187], v[176:179], v[92:95]
	ds_read_b64_tr_b16 v[184:185], v159 offset:26176
	ds_read_b64_tr_b16 v[186:187], v159 offset:27264
	s_waitcnt lgkmcnt(0)
	v_mfma_f32_16x16x32_bf16 v[92:95], v[184:187], v[180:183], v[92:95]
	s_waitcnt vmcnt(21)
	v_lshlrev_b32_e32 v184, 16, v88
	v_and_b32_e32 v88, 0xffff0000, v88
	s_nop 4
	v_add_f32_e32 v92, v167, v92
	v_add_f32_e32 v93, v167, v93
	v_mul_f32_e32 v92, v92, v184
	s_waitcnt vmcnt(20)
	v_lshlrev_b32_e32 v184, 16, v68
	v_mul_f32_e32 v88, v93, v88
	v_and_b32_e32 v68, 0xffff0000, v68
	v_mul_f32_e32 v68, v88, v68
	v_lshlrev_b32_e32 v88, 16, v89
	v_add_f32_e32 v93, v167, v94
	v_mul_f32_e32 v88, v93, v88
	v_lshlrev_b32_e32 v93, 16, v69
	v_mul_f32_e32 v88, v88, v93
	v_and_b32_e32 v89, 0xffff0000, v89
	v_add_f32_e32 v93, v167, v95
	v_mul_f32_e32 v89, v93, v89
	v_and_b32_e32 v69, 0xffff0000, v69
	v_mul_f32_e32 v92, v92, v184
	v_mul_f32_e32 v69, v89, v69
	v_cvt_pk_bf16_f32 v68, v92, v68
	v_cvt_pk_bf16_f32 v69, v88, v69
	ds_read_b64_tr_b16 v[92:93], v159 offset:72
	ds_read_b64_tr_b16 v[94:95], v159 offset:1160
	ds_read_b64_tr_b16 v[184:185], v159 offset:8776
	ds_read_b64_tr_b16 v[186:187], v159 offset:9864
	s_waitcnt lgkmcnt(2)
	v_mfma_f32_16x16x32_bf16 v[92:95], v[92:95], v[168:171], 0
	v_lshlrev_b32_e32 v88, 16, v90
	s_waitcnt lgkmcnt(0)
	v_mfma_f32_16x16x32_bf16 v[92:95], v[184:187], v[172:175], v[92:95]
	ds_read_b64_tr_b16 v[184:185], v159 offset:17480
	ds_read_b64_tr_b16 v[186:187], v159 offset:18568
	s_waitcnt lgkmcnt(0)
	v_mfma_f32_16x16x32_bf16 v[92:95], v[184:187], v[176:179], v[92:95]
	ds_read_b64_tr_b16 v[184:185], v159 offset:26184
	ds_read_b64_tr_b16 v[186:187], v159 offset:27272
	s_waitcnt lgkmcnt(0)
	v_mfma_f32_16x16x32_bf16 v[92:95], v[184:187], v[180:183], v[92:95]
	s_nop 7
	v_add_f32_e32 v89, v167, v92
	v_mul_f32_e32 v88, v89, v88
	v_lshlrev_b32_e32 v89, 16, v70
	v_mul_f32_e32 v88, v88, v89
	v_and_b32_e32 v89, 0xffff0000, v90
	v_add_f32_e32 v90, v167, v93
	v_mul_f32_e32 v89, v90, v89
	v_and_b32_e32 v70, 0xffff0000, v70
	v_mul_f32_e32 v70, v89, v70
	v_lshlrev_b32_e32 v89, 16, v91
	v_add_f32_e32 v90, v167, v94
	v_mul_f32_e32 v89, v90, v89
	v_lshlrev_b32_e32 v90, 16, v71
	v_mul_f32_e32 v89, v89, v90
	v_and_b32_e32 v90, 0xffff0000, v91
	v_add_f32_e32 v91, v167, v95
	v_mul_f32_e32 v90, v91, v90
	v_and_b32_e32 v71, 0xffff0000, v71
	v_mul_f32_e32 v71, v90, v71
	v_cvt_pk_bf16_f32 v70, v88, v70
	v_cvt_pk_bf16_f32 v71, v89, v71
	ds_read_b64_tr_b16 v[88:89], v159 offset:128
	ds_read_b64_tr_b16 v[90:91], v159 offset:1216
	ds_read_b64_tr_b16 v[92:93], v159 offset:8832
	ds_read_b64_tr_b16 v[94:95], v159 offset:9920
	s_waitcnt lgkmcnt(2)
	v_mfma_f32_16x16x32_bf16 v[88:91], v[88:91], v[168:171], 0
	s_waitcnt lgkmcnt(0)
	v_mfma_f32_16x16x32_bf16 v[88:91], v[92:95], v[172:175], v[88:91]
	ds_read_b64_tr_b16 v[92:93], v159 offset:17536
	ds_read_b64_tr_b16 v[94:95], v159 offset:18624
	s_waitcnt lgkmcnt(0)
	v_mfma_f32_16x16x32_bf16 v[88:91], v[92:95], v[176:179], v[88:91]
	ds_read_b64_tr_b16 v[92:93], v159 offset:26240
	ds_read_b64_tr_b16 v[94:95], v159 offset:27328
	s_waitcnt lgkmcnt(0)
	v_mfma_f32_16x16x32_bf16 v[88:91], v[92:95], v[180:183], v[88:91]
	s_waitcnt vmcnt(19)
	v_lshlrev_b32_e32 v92, 16, v84
	v_and_b32_e32 v84, 0xffff0000, v84
	s_nop 4
	v_add_f32_e32 v88, v167, v88
	v_add_f32_e32 v89, v167, v89
	v_mul_f32_e32 v88, v88, v92
	s_waitcnt vmcnt(18)
	v_lshlrev_b32_e32 v92, 16, v72
	v_mul_f32_e32 v84, v89, v84
	v_and_b32_e32 v72, 0xffff0000, v72
	v_mul_f32_e32 v72, v84, v72
	v_lshlrev_b32_e32 v84, 16, v85
	v_add_f32_e32 v89, v167, v90
	v_mul_f32_e32 v84, v89, v84
	v_lshlrev_b32_e32 v89, 16, v73
	v_mul_f32_e32 v84, v84, v89
	v_and_b32_e32 v85, 0xffff0000, v85
	v_add_f32_e32 v89, v167, v91
	v_mul_f32_e32 v85, v89, v85
	v_and_b32_e32 v73, 0xffff0000, v73
	v_mul_f32_e32 v88, v88, v92
	v_mul_f32_e32 v73, v85, v73
	v_cvt_pk_bf16_f32 v72, v88, v72
	v_cvt_pk_bf16_f32 v73, v84, v73
	ds_read_b64_tr_b16 v[88:89], v159 offset:136
	ds_read_b64_tr_b16 v[90:91], v159 offset:1224
	ds_read_b64_tr_b16 v[92:93], v159 offset:8840
	ds_read_b64_tr_b16 v[94:95], v159 offset:9928
	s_waitcnt lgkmcnt(2)
	v_mfma_f32_16x16x32_bf16 v[88:91], v[88:91], v[168:171], 0
	v_lshlrev_b32_e32 v84, 16, v86
	s_waitcnt lgkmcnt(0)
	v_mfma_f32_16x16x32_bf16 v[88:91], v[92:95], v[172:175], v[88:91]
	ds_read_b64_tr_b16 v[92:93], v159 offset:17544
	ds_read_b64_tr_b16 v[94:95], v159 offset:18632
	s_waitcnt lgkmcnt(0)
	v_mfma_f32_16x16x32_bf16 v[88:91], v[92:95], v[176:179], v[88:91]
	ds_read_b64_tr_b16 v[92:93], v159 offset:26248
	ds_read_b64_tr_b16 v[94:95], v159 offset:27336
	s_waitcnt lgkmcnt(0)
	v_mfma_f32_16x16x32_bf16 v[88:91], v[92:95], v[180:183], v[88:91]
	s_nop 7
	v_add_f32_e32 v85, v167, v88
	v_mul_f32_e32 v84, v85, v84
	v_lshlrev_b32_e32 v85, 16, v74
	v_mul_f32_e32 v84, v84, v85
	v_and_b32_e32 v85, 0xffff0000, v86
	v_add_f32_e32 v86, v167, v89
	v_mul_f32_e32 v85, v86, v85
	v_and_b32_e32 v74, 0xffff0000, v74
	v_mul_f32_e32 v74, v85, v74
	v_lshlrev_b32_e32 v85, 16, v87
	v_add_f32_e32 v86, v167, v90
	v_mul_f32_e32 v85, v86, v85
	v_lshlrev_b32_e32 v86, 16, v75
	v_mul_f32_e32 v85, v85, v86
	v_and_b32_e32 v86, 0xffff0000, v87
	v_add_f32_e32 v87, v167, v91
	v_mul_f32_e32 v86, v87, v86
	v_and_b32_e32 v75, 0xffff0000, v75
	v_mul_f32_e32 v75, v86, v75
	v_cvt_pk_bf16_f32 v74, v84, v74
	v_cvt_pk_bf16_f32 v75, v85, v75
	ds_read_b64_tr_b16 v[84:85], v159 offset:192
	ds_read_b64_tr_b16 v[86:87], v159 offset:1280
	ds_read_b64_tr_b16 v[88:89], v159 offset:8896
	ds_read_b64_tr_b16 v[90:91], v159 offset:9984
	s_waitcnt lgkmcnt(2)
	v_mfma_f32_16x16x32_bf16 v[84:87], v[84:87], v[168:171], 0
	s_waitcnt lgkmcnt(0)
	v_mfma_f32_16x16x32_bf16 v[84:87], v[88:91], v[172:175], v[84:87]
	ds_read_b64_tr_b16 v[88:89], v159 offset:17600
	ds_read_b64_tr_b16 v[90:91], v159 offset:18688
	s_waitcnt lgkmcnt(0)
	v_mfma_f32_16x16x32_bf16 v[84:87], v[88:91], v[176:179], v[84:87]
	ds_read_b64_tr_b16 v[88:89], v159 offset:26304
	ds_read_b64_tr_b16 v[90:91], v159 offset:27392
	s_waitcnt lgkmcnt(0)
	v_mfma_f32_16x16x32_bf16 v[84:87], v[88:91], v[180:183], v[84:87]
	s_waitcnt vmcnt(17)
	v_lshlrev_b32_e32 v88, 16, v80
	v_and_b32_e32 v80, 0xffff0000, v80
	s_nop 4
	v_add_f32_e32 v84, v167, v84
	v_add_f32_e32 v85, v167, v85
	v_mul_f32_e32 v84, v84, v88
	s_waitcnt vmcnt(16)
	v_lshlrev_b32_e32 v88, 16, v76
	v_mul_f32_e32 v80, v85, v80
	v_and_b32_e32 v76, 0xffff0000, v76
	v_mul_f32_e32 v76, v80, v76
	v_lshlrev_b32_e32 v80, 16, v81
	v_add_f32_e32 v85, v167, v86
	v_mul_f32_e32 v80, v85, v80
	v_lshlrev_b32_e32 v85, 16, v77
	v_mul_f32_e32 v80, v80, v85
	v_and_b32_e32 v81, 0xffff0000, v81
	v_add_f32_e32 v85, v167, v87
	v_mul_f32_e32 v81, v85, v81
	v_and_b32_e32 v77, 0xffff0000, v77
	v_mul_f32_e32 v84, v84, v88
	v_mul_f32_e32 v77, v81, v77
	v_cvt_pk_bf16_f32 v76, v84, v76
	v_cvt_pk_bf16_f32 v77, v80, v77
	ds_read_b64_tr_b16 v[84:85], v159 offset:200
	ds_read_b64_tr_b16 v[86:87], v159 offset:1288
	ds_read_b64_tr_b16 v[88:89], v159 offset:8904
	ds_read_b64_tr_b16 v[90:91], v159 offset:9992
	s_waitcnt lgkmcnt(2)
	v_mfma_f32_16x16x32_bf16 v[84:87], v[84:87], v[168:171], 0
	v_lshlrev_b32_e32 v80, 16, v82
	s_waitcnt lgkmcnt(0)
	v_mfma_f32_16x16x32_bf16 v[84:87], v[88:91], v[172:175], v[84:87]
	ds_read_b64_tr_b16 v[88:89], v159 offset:17608
	ds_read_b64_tr_b16 v[90:91], v159 offset:18696
	s_waitcnt lgkmcnt(0)
	v_mfma_f32_16x16x32_bf16 v[84:87], v[88:91], v[176:179], v[84:87]
	ds_read_b64_tr_b16 v[88:89], v159 offset:26312
	ds_read_b64_tr_b16 v[90:91], v159 offset:27400
	s_waitcnt lgkmcnt(0)
	v_mfma_f32_16x16x32_bf16 v[84:87], v[88:91], v[180:183], v[84:87]
	s_nop 7
	v_add_f32_e32 v81, v167, v84
	v_mul_f32_e32 v80, v81, v80
	v_lshlrev_b32_e32 v81, 16, v78
	v_mul_f32_e32 v80, v80, v81
	v_and_b32_e32 v81, 0xffff0000, v82
	v_add_f32_e32 v82, v167, v85
	v_mul_f32_e32 v81, v82, v81
	v_and_b32_e32 v78, 0xffff0000, v78
	v_mul_f32_e32 v78, v81, v78
	v_lshlrev_b32_e32 v81, 16, v83
	v_add_f32_e32 v82, v167, v86
	v_mul_f32_e32 v81, v82, v81
	v_lshlrev_b32_e32 v82, 16, v79
	v_mul_f32_e32 v81, v81, v82
	v_and_b32_e32 v82, 0xffff0000, v83
	v_add_f32_e32 v83, v167, v87
	v_mul_f32_e32 v82, v83, v82
	v_and_b32_e32 v79, 0xffff0000, v79
	v_mul_f32_e32 v79, v82, v79
	v_cvt_pk_bf16_f32 v78, v80, v78
	v_cvt_pk_bf16_f32 v79, v81, v79
	v_lshl_add_u64 v[80:81], s[4:5], 0, v[148:149]
	v_lshl_add_u64 v[148:149], v[80:81], 0, v[102:103]
	global_store_dwordx4 v[148:149], v[64:67], off
	global_store_dwordx4 v[148:149], v[68:71], off offset:64
	global_store_dwordx4 v[148:149], v[72:75], off offset:128
	global_store_dwordx4 v[148:149], v[76:79], off offset:192
	s_barrier
	s_waitcnt vmcnt(19)
	ds_write_b128 v160, v[48:51] offset:32768
	s_waitcnt vmcnt(14)
	ds_write_b128 v161, v[52:55] offset:32768
	s_waitcnt vmcnt(13)
	ds_write_b128 v162, v[56:59] offset:32768
	s_waitcnt vmcnt(12)
	ds_write_b128 v163, v[60:63] offset:32768
	v_and_b32_e32 v49, 0xffff0000, v44
	v_and_b32_e32 v51, 0xffff0000, v45
	v_lshlrev_b32_e32 v48, 16, v44
	v_mul_f32_e32 v44, v49, v49
	v_lshlrev_b32_e32 v50, 16, v45
	v_mul_f32_e32 v45, v51, v51
	v_fmac_f32_e32 v44, v48, v48
	v_fmac_f32_e32 v45, v50, v50
	v_and_b32_e32 v53, 0xffff0000, v46
	v_add_f32_e32 v44, v44, v45
	v_lshlrev_b32_e32 v52, 16, v46
	v_mul_f32_e32 v45, v53, v53
	v_fmac_f32_e32 v45, v52, v52
	v_and_b32_e32 v55, 0xffff0000, v47
	v_add_f32_e32 v44, v45, v44
	v_lshlrev_b32_e32 v54, 16, v47
	v_mul_f32_e32 v45, v55, v55
	v_and_b32_e32 v57, 0xffff0000, v40
	v_fmac_f32_e32 v45, v54, v54
	v_lshlrev_b32_e32 v56, 16, v40
	v_mul_f32_e32 v40, v57, v57
	v_and_b32_e32 v59, 0xffff0000, v41
	v_add_f32_e32 v44, v45, v44
	v_fmac_f32_e32 v40, v56, v56
	v_lshlrev_b32_e32 v58, 16, v41
	v_mul_f32_e32 v41, v59, v59
	v_add_f32_e32 v40, v40, v44
	v_fmac_f32_e32 v41, v58, v58
	v_and_b32_e32 v61, 0xffff0000, v42
	v_add_f32_e32 v40, v41, v40
	v_lshlrev_b32_e32 v60, 16, v42
	v_mul_f32_e32 v41, v61, v61
	v_fmac_f32_e32 v41, v60, v60
	v_and_b32_e32 v63, 0xffff0000, v43
	v_add_f32_e32 v40, v41, v40
	v_lshlrev_b32_e32 v62, 16, v43
	v_mul_f32_e32 v41, v63, v63
	v_and_b32_e32 v65, 0xffff0000, v36
	v_fmac_f32_e32 v41, v62, v62
	v_lshlrev_b32_e32 v64, 16, v36
	v_mul_f32_e32 v36, v65, v65
	v_and_b32_e32 v67, 0xffff0000, v37
	v_add_f32_e32 v40, v41, v40
	v_fmac_f32_e32 v36, v64, v64
	v_lshlrev_b32_e32 v66, 16, v37
	v_mul_f32_e32 v37, v67, v67
	v_add_f32_e32 v36, v36, v40
	v_fmac_f32_e32 v37, v66, v66
	v_and_b32_e32 v69, 0xffff0000, v38
	v_add_f32_e32 v36, v37, v36
	v_lshlrev_b32_e32 v68, 16, v38
	v_mul_f32_e32 v37, v69, v69
	v_fmac_f32_e32 v37, v68, v68
	v_and_b32_e32 v71, 0xffff0000, v39
	v_add_f32_e32 v36, v37, v36
	v_lshlrev_b32_e32 v70, 16, v39
	v_mul_f32_e32 v37, v71, v71
	v_and_b32_e32 v43, 0xffff0000, v33
	v_and_b32_e32 v42, 0xffff0000, v32
	v_fmac_f32_e32 v37, v70, v70
	v_lshlrev_b32_e32 v41, 16, v33
	v_lshlrev_b32_e32 v40, 16, v32
	v_pk_mul_f32 v[32:33], v[42:43], v[42:43]
	v_add_f32_e32 v36, v37, v36
	v_pk_fma_f32 v[32:33], v[40:41], v[40:41], v[32:33]
	v_and_b32_e32 v47, 0xffff0000, v35
	v_add_f32_e32 v32, v32, v36
	v_and_b32_e32 v46, 0xffff0000, v34
	v_add_f32_e32 v36, v33, v32
	v_lshlrev_b32_e32 v45, 16, v35
	v_lshlrev_b32_e32 v44, 16, v34
	v_pk_mul_f32 v[32:33], v[46:47], v[46:47]
	s_nop 0
	v_pk_fma_f32 v[32:33], v[44:45], v[44:45], v[32:33]
	s_nop 0
	v_add_f32_e32 v32, v32, v36
	v_add_f32_e32 v32, v33, v32
	ds_bpermute_b32 v33, v155, v32
	s_waitcnt lgkmcnt(0)
	v_add_f32_e32 v32, v32, v33
	ds_bpermute_b32 v33, v156, v32
	s_waitcnt lgkmcnt(0)
	v_add_f32_e32 v32, v32, v33
	v_fmamk_f32 v32, v32, 0x3c000000, v164
	v_rsq_f32_e32 v72, v32
	ds_read_b128 v[32:35], v157 offset:512
	ds_read_b128 v[36:39], v157 offset:528
	v_mul_f32_e32 v48, v72, v48
	s_waitcnt lgkmcnt(1)
	v_mul_f32_e32 v32, v32, v48
	v_mul_f32_e32 v48, v72, v49
	v_mul_f32_e32 v33, v33, v48
	v_cvt_pk_bf16_f32 v32, v32, v33
	v_mul_f32_e32 v33, v72, v50
	v_mul_f32_e32 v33, v34, v33
	v_mul_f32_e32 v34, v72, v51
	v_mul_f32_e32 v34, v35, v34
	v_cvt_pk_bf16_f32 v33, v33, v34
	v_mul_f32_e32 v34, v72, v52
	v_mul_f32_e32 v35, v72, v53
	s_waitcnt lgkmcnt(0)
	v_mul_f32_e32 v34, v36, v34
	v_mul_f32_e32 v35, v37, v35
	v_cvt_pk_bf16_f32 v34, v34, v35
	v_mul_f32_e32 v35, v72, v54
	v_mul_f32_e32 v35, v38, v35
	v_mul_f32_e32 v36, v72, v55
	v_mul_f32_e32 v36, v39, v36
	v_cvt_pk_bf16_f32 v35, v35, v36
	ds_write_b128 v165, v[32:35]
	ds_read_b128 v[32:35], v157 offset:544
	ds_read_b128 v[36:39], v157 offset:560
	v_mul_f32_e32 v48, v72, v56
	v_mul_f32_e32 v40, v72, v40
	s_waitcnt lgkmcnt(1)
	v_mul_f32_e32 v32, v48, v32
	v_mul_f32_e32 v48, v72, v57
	v_mul_f32_e32 v33, v48, v33
	v_cvt_pk_bf16_f32 v32, v32, v33
	v_mul_f32_e32 v33, v72, v58
	v_mul_f32_e32 v33, v33, v34
	v_mul_f32_e32 v34, v72, v59
	v_mul_f32_e32 v34, v34, v35
	v_cvt_pk_bf16_f32 v33, v33, v34
	v_mul_f32_e32 v34, v72, v60
	v_mul_f32_e32 v35, v72, v61
	s_waitcnt lgkmcnt(0)
	v_mul_f32_e32 v34, v34, v36
	v_mul_f32_e32 v35, v35, v37
	v_cvt_pk_bf16_f32 v34, v34, v35
	v_mul_f32_e32 v35, v72, v62
	v_mul_f32_e32 v35, v35, v38
	v_mul_f32_e32 v36, v72, v63
	v_mul_f32_e32 v36, v36, v39
	v_cvt_pk_bf16_f32 v35, v35, v36
	ds_write_b128 v165, v[32:35] offset:16
	ds_read_b128 v[32:35], v157 offset:576
	ds_read_b128 v[36:39], v157 offset:592
	v_mul_f32_e32 v48, v72, v64
	s_waitcnt lgkmcnt(1)
	v_mul_f32_e32 v32, v48, v32
	v_mul_f32_e32 v48, v72, v65
	v_mul_f32_e32 v33, v48, v33
	v_cvt_pk_bf16_f32 v32, v32, v33
	v_mul_f32_e32 v33, v72, v66
	v_mul_f32_e32 v33, v33, v34
	v_mul_f32_e32 v34, v72, v67
	v_mul_f32_e32 v34, v34, v35
	v_cvt_pk_bf16_f32 v33, v33, v34
	v_mul_f32_e32 v34, v72, v68
	v_mul_f32_e32 v35, v72, v69
	s_waitcnt lgkmcnt(0)
	v_mul_f32_e32 v34, v34, v36
	v_mul_f32_e32 v35, v35, v37
	v_cvt_pk_bf16_f32 v34, v34, v35
	v_mul_f32_e32 v35, v72, v70
	v_mul_f32_e32 v35, v35, v38
	v_mul_f32_e32 v36, v72, v71
	v_mul_f32_e32 v36, v36, v39
	v_cvt_pk_bf16_f32 v35, v35, v36
	ds_write_b128 v165, v[32:35] offset:32
	ds_read_b128 v[32:35], v157 offset:608
	ds_read_b128 v[36:39], v157 offset:624
	s_waitcnt lgkmcnt(1)
	v_mul_f32_e32 v32, v40, v32
	v_mul_f32_e32 v40, v72, v42
	v_mul_f32_e32 v33, v40, v33
	v_cvt_pk_bf16_f32 v32, v32, v33
	v_mul_f32_e32 v33, v72, v41
	v_mul_f32_e32 v33, v33, v34
	v_mul_f32_e32 v34, v72, v43
	v_mul_f32_e32 v34, v34, v35
	v_cvt_pk_bf16_f32 v33, v33, v34
	v_mul_f32_e32 v34, v72, v44
	v_mul_f32_e32 v35, v72, v46
	s_waitcnt lgkmcnt(0)
	v_mul_f32_e32 v34, v34, v36
	v_mul_f32_e32 v35, v35, v37
	v_cvt_pk_bf16_f32 v34, v34, v35
	v_mul_f32_e32 v35, v72, v45
	v_mul_f32_e32 v35, v35, v38
	v_mul_f32_e32 v36, v72, v47
	v_mul_f32_e32 v36, v36, v39
	v_cvt_pk_bf16_f32 v35, v35, v36
	ds_write_b128 v165, v[32:35] offset:48
	s_waitcnt lgkmcnt(0)
	s_barrier
	global_load_dwordx4 v[80:83], v[120:121], off
	global_load_dwordx4 v[64:67], v[142:143], off offset:560
	global_load_dwordx4 v[68:71], v[142:143], off offset:544
	global_load_dwordx4 v[72:75], v[142:143], off offset:528
	global_load_dwordx4 v[76:79], v[142:143], off offset:512
	global_load_dwordx4 v[84:87], v[122:123], off
	global_load_dwordx4 v[88:91], v[124:125], off
	global_load_dwordx4 v[92:95], v[126:127], off
	global_load_dwordx4 v[60:63], v[144:145], off offset:512
	global_load_dwordx4 v[56:59], v[146:147], off offset:512
	global_load_dwordx4 v[52:55], v[144:145], off offset:576
	global_load_dwordx4 v[48:51], v[146:147], off offset:576
	global_load_dwordx4 v[44:47], v[144:145], off offset:640
	global_load_dwordx4 v[40:43], v[146:147], off offset:640
	global_load_dwordx4 v[36:39], v[144:145], off offset:704
	global_load_dwordx4 v[32:35], v[146:147], off offset:704
	ds_read_b128 v[168:171], v166 offset:32768
	ds_read_b128 v[172:175], v166 offset:32832
	ds_read_b128 v[176:179], v166 offset:32896
	ds_read_b128 v[180:183], v166 offset:32960
	ds_read_b32 v167, v158 offset:2560
	ds_read_b64_tr_b16 v[184:185], v159
	ds_read_b64_tr_b16 v[186:187], v159 offset:1088
	ds_read_b64_tr_b16 v[188:189], v159 offset:8704
	ds_read_b64_tr_b16 v[190:191], v159 offset:9792
	s_waitcnt lgkmcnt(2)
	v_mfma_f32_16x16x32_bf16 v[184:187], v[184:187], v[168:171], 0
	s_waitcnt lgkmcnt(0)
	v_mfma_f32_16x16x32_bf16 v[184:187], v[188:191], v[172:175], v[184:187]
	ds_read_b64_tr_b16 v[188:189], v159 offset:17408
	ds_read_b64_tr_b16 v[190:191], v159 offset:18496
	s_waitcnt lgkmcnt(0)
	v_mfma_f32_16x16x32_bf16 v[184:187], v[188:191], v[176:179], v[184:187]
	ds_read_b64_tr_b16 v[188:189], v159 offset:26112
	ds_read_b64_tr_b16 v[190:191], v159 offset:27200
	s_waitcnt lgkmcnt(0)
	v_mfma_f32_16x16x32_bf16 v[184:187], v[188:191], v[180:183], v[184:187]
	s_waitcnt vmcnt(27)
	v_lshlrev_b32_e32 v188, 16, v28
	v_and_b32_e32 v28, 0xffff0000, v28
	s_nop 4
	v_add_f32_e32 v184, v167, v184
	v_add_f32_e32 v185, v167, v185
	v_mul_f32_e32 v184, v184, v188
	s_waitcnt vmcnt(26)
	v_lshlrev_b32_e32 v188, 16, v24
	v_mul_f32_e32 v28, v185, v28
	v_and_b32_e32 v24, 0xffff0000, v24
	v_mul_f32_e32 v24, v28, v24
	v_lshlrev_b32_e32 v28, 16, v29
	v_add_f32_e32 v185, v167, v186
	v_mul_f32_e32 v28, v185, v28
	v_lshlrev_b32_e32 v185, 16, v25
	v_mul_f32_e32 v28, v28, v185
	v_and_b32_e32 v29, 0xffff0000, v29
	v_add_f32_e32 v185, v167, v187
	v_mul_f32_e32 v29, v185, v29
	v_and_b32_e32 v25, 0xffff0000, v25
	v_mul_f32_e32 v184, v184, v188
	v_mul_f32_e32 v25, v29, v25
	v_cvt_pk_bf16_f32 v24, v184, v24
	v_cvt_pk_bf16_f32 v25, v28, v25
	ds_read_b64_tr_b16 v[184:185], v159 offset:8
	ds_read_b64_tr_b16 v[186:187], v159 offset:1096
	ds_read_b64_tr_b16 v[188:189], v159 offset:8712
	ds_read_b64_tr_b16 v[190:191], v159 offset:9800
	s_waitcnt lgkmcnt(2)
	v_mfma_f32_16x16x32_bf16 v[184:187], v[184:187], v[168:171], 0
	v_lshlrev_b32_e32 v28, 16, v30
	s_waitcnt lgkmcnt(0)
	v_mfma_f32_16x16x32_bf16 v[184:187], v[188:191], v[172:175], v[184:187]
	ds_read_b64_tr_b16 v[188:189], v159 offset:17416
	ds_read_b64_tr_b16 v[190:191], v159 offset:18504
	s_waitcnt lgkmcnt(0)
	v_mfma_f32_16x16x32_bf16 v[184:187], v[188:191], v[176:179], v[184:187]
	ds_read_b64_tr_b16 v[188:189], v159 offset:26120
	ds_read_b64_tr_b16 v[190:191], v159 offset:27208
	s_waitcnt lgkmcnt(0)
	v_mfma_f32_16x16x32_bf16 v[184:187], v[188:191], v[180:183], v[184:187]
	s_nop 7
	v_add_f32_e32 v29, v167, v184
	v_mul_f32_e32 v28, v29, v28
	v_lshlrev_b32_e32 v29, 16, v26
	v_mul_f32_e32 v28, v28, v29
	v_and_b32_e32 v29, 0xffff0000, v30
	v_add_f32_e32 v30, v167, v185
	v_mul_f32_e32 v29, v30, v29
	v_and_b32_e32 v26, 0xffff0000, v26
	v_mul_f32_e32 v26, v29, v26
	v_lshlrev_b32_e32 v29, 16, v31
	v_add_f32_e32 v30, v167, v186
	v_mul_f32_e32 v29, v30, v29
	v_lshlrev_b32_e32 v30, 16, v27
	v_mul_f32_e32 v29, v29, v30
	v_and_b32_e32 v30, 0xffff0000, v31
	v_add_f32_e32 v31, v167, v187
	v_mul_f32_e32 v30, v31, v30
	v_and_b32_e32 v27, 0xffff0000, v27
	v_mul_f32_e32 v27, v30, v27
	v_cvt_pk_bf16_f32 v26, v28, v26
	v_cvt_pk_bf16_f32 v27, v29, v27
	ds_read_b64_tr_b16 v[28:29], v159 offset:64
	ds_read_b64_tr_b16 v[30:31], v159 offset:1152
	ds_read_b64_tr_b16 v[184:185], v159 offset:8768
	ds_read_b64_tr_b16 v[186:187], v159 offset:9856
	s_waitcnt lgkmcnt(2)
	v_mfma_f32_16x16x32_bf16 v[28:31], v[28:31], v[168:171], 0
	s_waitcnt lgkmcnt(0)
	v_mfma_f32_16x16x32_bf16 v[28:31], v[184:187], v[172:175], v[28:31]
	ds_read_b64_tr_b16 v[184:185], v159 offset:17472
	ds_read_b64_tr_b16 v[186:187], v159 offset:18560
	s_waitcnt lgkmcnt(0)
	v_mfma_f32_16x16x32_bf16 v[28:31], v[184:187], v[176:179], v[28:31]
	ds_read_b64_tr_b16 v[184:185], v159 offset:26176
	ds_read_b64_tr_b16 v[186:187], v159 offset:27264
	s_waitcnt lgkmcnt(0)
	v_mfma_f32_16x16x32_bf16 v[28:31], v[184:187], v[180:183], v[28:31]
	s_waitcnt vmcnt(25)
	v_lshlrev_b32_e32 v184, 16, v20
	v_and_b32_e32 v20, 0xffff0000, v20
	s_nop 4
	v_add_f32_e32 v28, v167, v28
	v_add_f32_e32 v29, v167, v29
	v_mul_f32_e32 v28, v28, v184
	s_waitcnt vmcnt(24)
	v_lshlrev_b32_e32 v184, 16, v16
	v_mul_f32_e32 v20, v29, v20
	v_and_b32_e32 v16, 0xffff0000, v16
	v_mul_f32_e32 v16, v20, v16
	v_lshlrev_b32_e32 v20, 16, v21
	v_add_f32_e32 v29, v167, v30
	v_mul_f32_e32 v20, v29, v20
	v_lshlrev_b32_e32 v29, 16, v17
	v_mul_f32_e32 v20, v20, v29
	v_and_b32_e32 v21, 0xffff0000, v21
	v_add_f32_e32 v29, v167, v31
	v_mul_f32_e32 v21, v29, v21
	v_and_b32_e32 v17, 0xffff0000, v17
	v_mul_f32_e32 v28, v28, v184
	v_mul_f32_e32 v17, v21, v17
	v_cvt_pk_bf16_f32 v16, v28, v16
	v_cvt_pk_bf16_f32 v17, v20, v17
	ds_read_b64_tr_b16 v[28:29], v159 offset:72
	ds_read_b64_tr_b16 v[30:31], v159 offset:1160
	ds_read_b64_tr_b16 v[184:185], v159 offset:8776
	ds_read_b64_tr_b16 v[186:187], v159 offset:9864
	s_waitcnt lgkmcnt(2)
	v_mfma_f32_16x16x32_bf16 v[28:31], v[28:31], v[168:171], 0
	v_lshlrev_b32_e32 v20, 16, v22
	s_waitcnt lgkmcnt(0)
	v_mfma_f32_16x16x32_bf16 v[28:31], v[184:187], v[172:175], v[28:31]
	ds_read_b64_tr_b16 v[184:185], v159 offset:17480
	ds_read_b64_tr_b16 v[186:187], v159 offset:18568
	s_waitcnt lgkmcnt(0)
	v_mfma_f32_16x16x32_bf16 v[28:31], v[184:187], v[176:179], v[28:31]
	ds_read_b64_tr_b16 v[184:185], v159 offset:26184
	ds_read_b64_tr_b16 v[186:187], v159 offset:27272
	s_waitcnt lgkmcnt(0)
	v_mfma_f32_16x16x32_bf16 v[28:31], v[184:187], v[180:183], v[28:31]
	s_nop 7
	v_add_f32_e32 v21, v167, v28
	v_mul_f32_e32 v20, v21, v20
	v_lshlrev_b32_e32 v21, 16, v18
	v_mul_f32_e32 v20, v20, v21
	v_and_b32_e32 v21, 0xffff0000, v22
	v_add_f32_e32 v22, v167, v29
	v_mul_f32_e32 v21, v22, v21
	v_and_b32_e32 v18, 0xffff0000, v18
	v_mul_f32_e32 v18, v21, v18
	v_lshlrev_b32_e32 v21, 16, v23
	v_add_f32_e32 v22, v167, v30
	v_mul_f32_e32 v21, v22, v21
	v_lshlrev_b32_e32 v22, 16, v19
	v_mul_f32_e32 v21, v21, v22
	v_and_b32_e32 v22, 0xffff0000, v23
	v_add_f32_e32 v23, v167, v31
	v_mul_f32_e32 v22, v23, v22
	v_and_b32_e32 v19, 0xffff0000, v19
	v_mul_f32_e32 v19, v22, v19
	v_cvt_pk_bf16_f32 v18, v20, v18
	v_cvt_pk_bf16_f32 v19, v21, v19
	ds_read_b64_tr_b16 v[20:21], v159 offset:128
	ds_read_b64_tr_b16 v[22:23], v159 offset:1216
	ds_read_b64_tr_b16 v[28:29], v159 offset:8832
	ds_read_b64_tr_b16 v[30:31], v159 offset:9920
	s_waitcnt lgkmcnt(2)
	v_mfma_f32_16x16x32_bf16 v[20:23], v[20:23], v[168:171], 0
	s_waitcnt lgkmcnt(0)
	v_mfma_f32_16x16x32_bf16 v[20:23], v[28:31], v[172:175], v[20:23]
	ds_read_b64_tr_b16 v[28:29], v159 offset:17536
	ds_read_b64_tr_b16 v[30:31], v159 offset:18624
	s_waitcnt lgkmcnt(0)
	v_mfma_f32_16x16x32_bf16 v[20:23], v[28:31], v[176:179], v[20:23]
	ds_read_b64_tr_b16 v[28:29], v159 offset:26240
	ds_read_b64_tr_b16 v[30:31], v159 offset:27328
	s_waitcnt lgkmcnt(0)
	v_mfma_f32_16x16x32_bf16 v[20:23], v[28:31], v[180:183], v[20:23]
	s_waitcnt vmcnt(23)
	v_lshlrev_b32_e32 v28, 16, v12
	v_and_b32_e32 v12, 0xffff0000, v12
	s_nop 4
	v_add_f32_e32 v20, v167, v20
	v_add_f32_e32 v21, v167, v21
	v_mul_f32_e32 v20, v20, v28
	s_waitcnt vmcnt(22)
	v_lshlrev_b32_e32 v28, 16, v8
	v_mul_f32_e32 v12, v21, v12
	v_and_b32_e32 v8, 0xffff0000, v8
	v_mul_f32_e32 v8, v12, v8
	v_lshlrev_b32_e32 v12, 16, v13
	v_add_f32_e32 v21, v167, v22
	v_mul_f32_e32 v12, v21, v12
	v_lshlrev_b32_e32 v21, 16, v9
	v_mul_f32_e32 v12, v12, v21
	v_and_b32_e32 v13, 0xffff0000, v13
	v_add_f32_e32 v21, v167, v23
	v_mul_f32_e32 v13, v21, v13
	v_and_b32_e32 v9, 0xffff0000, v9
	v_mul_f32_e32 v20, v20, v28
	v_mul_f32_e32 v9, v13, v9
	v_cvt_pk_bf16_f32 v8, v20, v8
	v_cvt_pk_bf16_f32 v9, v12, v9
	ds_read_b64_tr_b16 v[20:21], v159 offset:136
	ds_read_b64_tr_b16 v[22:23], v159 offset:1224
	ds_read_b64_tr_b16 v[28:29], v159 offset:8840
	ds_read_b64_tr_b16 v[30:31], v159 offset:9928
	s_waitcnt lgkmcnt(2)
	v_mfma_f32_16x16x32_bf16 v[20:23], v[20:23], v[168:171], 0
	v_lshlrev_b32_e32 v12, 16, v14
	s_waitcnt lgkmcnt(0)
	v_mfma_f32_16x16x32_bf16 v[20:23], v[28:31], v[172:175], v[20:23]
	ds_read_b64_tr_b16 v[28:29], v159 offset:17544
	ds_read_b64_tr_b16 v[30:31], v159 offset:18632
	s_waitcnt lgkmcnt(0)
	v_mfma_f32_16x16x32_bf16 v[20:23], v[28:31], v[176:179], v[20:23]
	ds_read_b64_tr_b16 v[28:29], v159 offset:26248
	ds_read_b64_tr_b16 v[30:31], v159 offset:27336
	s_waitcnt lgkmcnt(0)
	v_mfma_f32_16x16x32_bf16 v[20:23], v[28:31], v[180:183], v[20:23]
	s_waitcnt vmcnt(12)
	v_and_b32_e32 v29, 0xffff0000, v74
	v_lshlrev_b32_e32 v28, 16, v74
	v_and_b32_e32 v31, 0xffff0000, v75
	s_nop 3
	v_add_f32_e32 v13, v167, v20
	v_mul_f32_e32 v12, v13, v12
	v_lshlrev_b32_e32 v13, 16, v10
	v_mul_f32_e32 v12, v12, v13
	v_and_b32_e32 v13, 0xffff0000, v14
	v_add_f32_e32 v14, v167, v21
	v_mul_f32_e32 v13, v14, v13
	v_and_b32_e32 v10, 0xffff0000, v10
	v_mul_f32_e32 v10, v13, v10
	v_lshlrev_b32_e32 v13, 16, v15
	v_add_f32_e32 v14, v167, v22
	v_mul_f32_e32 v13, v14, v13
	v_lshlrev_b32_e32 v14, 16, v11
	v_mul_f32_e32 v13, v13, v14
	v_and_b32_e32 v14, 0xffff0000, v15
	v_add_f32_e32 v15, v167, v23
	v_mul_f32_e32 v14, v15, v14
	v_and_b32_e32 v11, 0xffff0000, v11
	v_mul_f32_e32 v11, v14, v11
	v_cvt_pk_bf16_f32 v10, v12, v10
	v_cvt_pk_bf16_f32 v11, v13, v11
	ds_read_b64_tr_b16 v[12:13], v159 offset:192
	ds_read_b64_tr_b16 v[14:15], v159 offset:1280
	ds_read_b64_tr_b16 v[20:21], v159 offset:8896
	ds_read_b64_tr_b16 v[22:23], v159 offset:9984
	s_waitcnt lgkmcnt(2)
	v_mfma_f32_16x16x32_bf16 v[12:15], v[12:15], v[168:171], 0
	v_lshlrev_b32_e32 v30, 16, v75
	v_lshlrev_b32_e32 v74, 16, v70
	v_and_b32_e32 v70, 0xffff0000, v70
	s_waitcnt lgkmcnt(0)
	v_mfma_f32_16x16x32_bf16 v[12:15], v[20:23], v[172:175], v[12:15]
	ds_read_b64_tr_b16 v[20:21], v159 offset:17600
	ds_read_b64_tr_b16 v[22:23], v159 offset:18688
	v_lshlrev_b32_e32 v75, 16, v71
	v_and_b32_e32 v71, 0xffff0000, v71
	s_waitcnt lgkmcnt(0)
	v_mfma_f32_16x16x32_bf16 v[12:15], v[20:23], v[176:179], v[12:15]
	ds_read_b64_tr_b16 v[20:21], v159 offset:26304
	ds_read_b64_tr_b16 v[22:23], v159 offset:27392
	s_waitcnt lgkmcnt(0)
	v_mfma_f32_16x16x32_bf16 v[12:15], v[20:23], v[180:183], v[12:15]
	v_lshlrev_b32_e32 v20, 16, v4
	v_and_b32_e32 v4, 0xffff0000, v4
	s_nop 5
	v_add_f32_e32 v12, v167, v12
	v_add_f32_e32 v13, v167, v13
	v_mul_f32_e32 v12, v12, v20
	v_lshlrev_b32_e32 v20, 16, v0
	v_mul_f32_e32 v4, v13, v4
	v_and_b32_e32 v0, 0xffff0000, v0
	v_mul_f32_e32 v0, v4, v0
	v_lshlrev_b32_e32 v4, 16, v5
	v_add_f32_e32 v13, v167, v14
	v_mul_f32_e32 v4, v13, v4
	v_lshlrev_b32_e32 v13, 16, v1
	v_mul_f32_e32 v4, v4, v13
	v_and_b32_e32 v5, 0xffff0000, v5
	v_add_f32_e32 v13, v167, v15
	v_mul_f32_e32 v5, v13, v5
	v_and_b32_e32 v1, 0xffff0000, v1
	v_mul_f32_e32 v12, v12, v20
	v_mul_f32_e32 v1, v5, v1
	v_cvt_pk_bf16_f32 v0, v12, v0
	v_cvt_pk_bf16_f32 v1, v4, v1
	ds_read_b64_tr_b16 v[12:13], v159 offset:200
	ds_read_b64_tr_b16 v[14:15], v159 offset:1288
	ds_read_b64_tr_b16 v[20:21], v159 offset:8904
	ds_read_b64_tr_b16 v[22:23], v159 offset:9992
	s_waitcnt lgkmcnt(2)
	v_mfma_f32_16x16x32_bf16 v[12:15], v[12:15], v[168:171], 0
	v_lshlrev_b32_e32 v4, 16, v6
	s_waitcnt lgkmcnt(0)
	v_mfma_f32_16x16x32_bf16 v[12:15], v[20:23], v[172:175], v[12:15]
	ds_read_b64_tr_b16 v[20:21], v159 offset:17608
	ds_read_b64_tr_b16 v[22:23], v159 offset:18696
	s_waitcnt lgkmcnt(0)
	v_mfma_f32_16x16x32_bf16 v[12:15], v[20:23], v[176:179], v[12:15]
	ds_read_b64_tr_b16 v[20:21], v159 offset:26312
	ds_read_b64_tr_b16 v[22:23], v159 offset:27400
	s_waitcnt lgkmcnt(0)
	v_mfma_f32_16x16x32_bf16 v[12:15], v[20:23], v[180:183], v[12:15]
	s_waitcnt vmcnt(11)
	v_and_b32_e32 v21, 0xffff0000, v78
	v_lshlrev_b32_e32 v20, 16, v78
	v_and_b32_e32 v23, 0xffff0000, v79
	s_nop 3
	v_add_f32_e32 v5, v167, v12
	v_mul_f32_e32 v4, v5, v4
	v_lshlrev_b32_e32 v5, 16, v2
	v_mul_f32_e32 v4, v4, v5
	v_and_b32_e32 v5, 0xffff0000, v6
	v_add_f32_e32 v6, v167, v13
	v_mul_f32_e32 v5, v6, v5
	v_and_b32_e32 v2, 0xffff0000, v2
	v_mul_f32_e32 v2, v5, v2
	v_lshlrev_b32_e32 v5, 16, v7
	v_add_f32_e32 v6, v167, v14
	v_mul_f32_e32 v5, v6, v5
	v_lshlrev_b32_e32 v6, 16, v3
	v_mul_f32_e32 v5, v5, v6
	v_and_b32_e32 v6, 0xffff0000, v7
	v_add_f32_e32 v7, v167, v15
	v_mul_f32_e32 v6, v7, v6
	v_and_b32_e32 v3, 0xffff0000, v3
	v_mul_f32_e32 v3, v6, v3
	v_cvt_pk_bf16_f32 v2, v4, v2
	v_cvt_pk_bf16_f32 v3, v5, v3
	global_store_dwordx4 v[148:149], v[24:27], off offset:256
	global_store_dwordx4 v[148:149], v[16:19], off offset:320
	global_store_dwordx4 v[148:149], v[8:11], off offset:384
	global_store_dwordx4 v[148:149], v[0:3], off offset:448
	v_and_b32_e32 v17, 0xffff0000, v76
	v_and_b32_e32 v19, 0xffff0000, v77
	v_lshlrev_b32_e32 v16, 16, v76
	v_mul_f32_e32 v0, v17, v17
	v_lshlrev_b32_e32 v18, 16, v77
	v_mul_f32_e32 v1, v19, v19
	v_fmac_f32_e32 v0, v16, v16
	v_fmac_f32_e32 v1, v18, v18
	v_add_f32_e32 v0, v0, v1
	v_mul_f32_e32 v1, v21, v21
	v_fmac_f32_e32 v1, v20, v20
	v_add_f32_e32 v0, v1, v0
	v_lshlrev_b32_e32 v22, 16, v79
	v_mul_f32_e32 v1, v23, v23
	v_fmac_f32_e32 v1, v22, v22
	v_and_b32_e32 v25, 0xffff0000, v72
	v_add_f32_e32 v0, v1, v0
	v_lshlrev_b32_e32 v24, 16, v72
	v_mul_f32_e32 v1, v25, v25
	v_fmac_f32_e32 v1, v24, v24
	v_and_b32_e32 v27, 0xffff0000, v73
	v_add_f32_e32 v0, v1, v0
	v_lshlrev_b32_e32 v26, 16, v73
	v_mul_f32_e32 v1, v27, v27
	v_fmac_f32_e32 v1, v26, v26
	v_add_f32_e32 v0, v1, v0
	v_mul_f32_e32 v1, v29, v29
	v_fmac_f32_e32 v1, v28, v28
	v_add_f32_e32 v0, v1, v0
	v_mul_f32_e32 v1, v31, v31
	v_fmac_f32_e32 v1, v30, v30
	v_lshlrev_b32_e32 v72, 16, v68
	v_and_b32_e32 v68, 0xffff0000, v68
	v_add_f32_e32 v0, v1, v0
	v_mul_f32_e32 v1, v68, v68
	v_fmac_f32_e32 v1, v72, v72
	v_lshlrev_b32_e32 v73, 16, v69
	v_and_b32_e32 v69, 0xffff0000, v69
	v_add_f32_e32 v0, v1, v0
	v_mul_f32_e32 v1, v69, v69
	v_fmac_f32_e32 v1, v73, v73
	v_add_f32_e32 v0, v1, v0
	v_mul_f32_e32 v1, v70, v70
	v_fmac_f32_e32 v1, v74, v74
	v_add_f32_e32 v0, v1, v0
	v_mul_f32_e32 v1, v71, v71
	v_fmac_f32_e32 v1, v75, v75
	v_and_b32_e32 v11, 0xffff0000, v65
	v_and_b32_e32 v10, 0xffff0000, v64
	v_add_f32_e32 v2, v1, v0
	v_lshlrev_b32_e32 v9, 16, v65
	v_lshlrev_b32_e32 v8, 16, v64
	v_pk_mul_f32 v[0:1], v[10:11], v[10:11]
	v_and_b32_e32 v15, 0xffff0000, v67
	v_pk_fma_f32 v[0:1], v[8:9], v[8:9], v[0:1]
	v_and_b32_e32 v14, 0xffff0000, v66
	v_add_f32_e32 v0, v0, v2
	v_add_f32_e32 v2, v1, v0
	v_lshlrev_b32_e32 v13, 16, v67
	v_lshlrev_b32_e32 v12, 16, v66
	v_pk_mul_f32 v[0:1], v[14:15], v[14:15]
	s_nop 0
	v_pk_fma_f32 v[0:1], v[12:13], v[12:13], v[0:1]
	s_barrier
	v_add_f32_e32 v0, v0, v2
	v_add_f32_e32 v0, v1, v0
	ds_bpermute_b32 v1, v155, v0
	s_waitcnt lgkmcnt(0)
	ds_write_b128 v160, v[80:83] offset:32768
	s_waitcnt vmcnt(14)
	ds_write_b128 v161, v[84:87] offset:32768
	s_waitcnt vmcnt(13)
	ds_write_b128 v162, v[88:91] offset:32768
	s_waitcnt vmcnt(12)
	ds_write_b128 v163, v[92:95] offset:32768
	v_add_f32_e32 v0, v0, v1
	ds_bpermute_b32 v1, v156, v0
	s_waitcnt lgkmcnt(0)
	v_add_f32_e32 v0, v0, v1
	v_fmamk_f32 v0, v0, 0x3c000000, v164
	v_rsq_f32_e32 v64, v0
	ds_read_b128 v[0:3], v157 offset:1024
	ds_read_b128 v[4:7], v157 offset:1040
	v_mul_f32_e32 v16, v64, v16
	s_waitcnt lgkmcnt(1)
	v_mul_f32_e32 v0, v0, v16
	v_mul_f32_e32 v16, v64, v17
	v_mul_f32_e32 v1, v1, v16
	v_cvt_pk_bf16_f32 v0, v0, v1
	v_mul_f32_e32 v1, v64, v18
	v_mul_f32_e32 v1, v2, v1
	v_mul_f32_e32 v2, v64, v19
	v_mul_f32_e32 v2, v3, v2
	v_cvt_pk_bf16_f32 v1, v1, v2
	v_mul_f32_e32 v2, v64, v20
	v_mul_f32_e32 v3, v64, v21
	s_waitcnt lgkmcnt(0)
	v_mul_f32_e32 v2, v4, v2
	v_mul_f32_e32 v3, v5, v3
	v_cvt_pk_bf16_f32 v2, v2, v3
	v_mul_f32_e32 v3, v64, v22
	v_mul_f32_e32 v3, v6, v3
	v_mul_f32_e32 v4, v64, v23
	v_mul_f32_e32 v4, v7, v4
	v_cvt_pk_bf16_f32 v3, v3, v4
	ds_write_b128 v165, v[0:3]
	ds_read_b128 v[0:3], v157 offset:1056
	ds_read_b128 v[4:7], v157 offset:1072
	v_mul_f32_e32 v16, v64, v24
	v_mul_f32_e32 v8, v64, v8
	s_waitcnt lgkmcnt(1)
	v_mul_f32_e32 v0, v16, v0
	v_mul_f32_e32 v16, v64, v25
	v_mul_f32_e32 v1, v16, v1
	v_cvt_pk_bf16_f32 v0, v0, v1
	v_mul_f32_e32 v1, v64, v26
	v_mul_f32_e32 v1, v1, v2
	v_mul_f32_e32 v2, v64, v27
	v_mul_f32_e32 v2, v2, v3
	v_cvt_pk_bf16_f32 v1, v1, v2
	v_mul_f32_e32 v2, v64, v28
	v_mul_f32_e32 v3, v64, v29
	s_waitcnt lgkmcnt(0)
	v_mul_f32_e32 v2, v2, v4
	v_mul_f32_e32 v3, v3, v5
	v_cvt_pk_bf16_f32 v2, v2, v3
	v_mul_f32_e32 v3, v64, v30
	v_mul_f32_e32 v3, v3, v6
	v_mul_f32_e32 v4, v64, v31
	v_mul_f32_e32 v4, v4, v7
	v_cvt_pk_bf16_f32 v3, v3, v4
	ds_write_b128 v165, v[0:3] offset:16
	ds_read_b128 v[0:3], v157 offset:1088
	ds_read_b128 v[4:7], v157 offset:1104
	v_mul_f32_e32 v16, v64, v72
	s_waitcnt lgkmcnt(1)
	v_mul_f32_e32 v0, v16, v0
	v_mul_f32_e32 v16, v64, v68
	v_mul_f32_e32 v1, v16, v1
	v_cvt_pk_bf16_f32 v0, v0, v1
	v_mul_f32_e32 v1, v64, v73
	v_mul_f32_e32 v1, v1, v2
	v_mul_f32_e32 v2, v64, v69
	v_mul_f32_e32 v2, v2, v3
	v_cvt_pk_bf16_f32 v1, v1, v2
	v_mul_f32_e32 v2, v64, v74
	v_mul_f32_e32 v3, v64, v70
	s_waitcnt lgkmcnt(0)
	v_mul_f32_e32 v2, v2, v4
	v_mul_f32_e32 v3, v3, v5
	v_cvt_pk_bf16_f32 v2, v2, v3
	v_mul_f32_e32 v3, v64, v75
	v_mul_f32_e32 v3, v3, v6
	v_mul_f32_e32 v4, v64, v71
	v_mul_f32_e32 v4, v4, v7
	v_cvt_pk_bf16_f32 v3, v3, v4
	ds_write_b128 v165, v[0:3] offset:32
	ds_read_b128 v[0:3], v157 offset:1120
	ds_read_b128 v[4:7], v157 offset:1136
	s_waitcnt lgkmcnt(1)
	v_mul_f32_e32 v0, v8, v0
	v_mul_f32_e32 v8, v64, v10
	v_mul_f32_e32 v1, v8, v1
	v_cvt_pk_bf16_f32 v0, v0, v1
	v_mul_f32_e32 v1, v64, v9
	v_mul_f32_e32 v1, v1, v2
	v_mul_f32_e32 v2, v64, v11
	v_mul_f32_e32 v2, v2, v3
	v_cvt_pk_bf16_f32 v1, v1, v2
	v_mul_f32_e32 v2, v64, v12
	v_mul_f32_e32 v3, v64, v14
	s_waitcnt lgkmcnt(0)
	v_mul_f32_e32 v2, v2, v4
	v_mul_f32_e32 v3, v3, v5
	v_cvt_pk_bf16_f32 v2, v2, v3
	v_mul_f32_e32 v3, v64, v13
	v_mul_f32_e32 v3, v3, v6
	v_mul_f32_e32 v4, v64, v15
	v_mul_f32_e32 v4, v4, v7
	v_cvt_pk_bf16_f32 v3, v3, v4
	ds_write_b128 v165, v[0:3] offset:48
	s_waitcnt lgkmcnt(0)
	s_barrier
	global_load_dwordx4 v[80:83], v[128:129], off
	global_load_dwordx4 v[64:67], v[142:143], off offset:816
	global_load_dwordx4 v[68:71], v[142:143], off offset:800
	global_load_dwordx4 v[72:75], v[142:143], off offset:784
	global_load_dwordx4 v[76:79], v[142:143], off offset:768
	global_load_dwordx4 v[84:87], v[130:131], off
	global_load_dwordx4 v[88:91], v[132:133], off
	global_load_dwordx4 v[92:95], v[134:135], off
	global_load_dwordx4 v[28:31], v[144:145], off offset:768
	global_load_dwordx4 v[24:27], v[146:147], off offset:768
	global_load_dwordx4 v[20:23], v[144:145], off offset:832
	global_load_dwordx4 v[16:19], v[146:147], off offset:832
	global_load_dwordx4 v[12:15], v[144:145], off offset:896
	global_load_dwordx4 v[8:11], v[146:147], off offset:896
	global_load_dwordx4 v[4:7], v[144:145], off offset:960
	global_load_dwordx4 v[0:3], v[146:147], off offset:960
	ds_read_b128 v[142:145], v166 offset:32768
	ds_read_b128 v[168:171], v166 offset:32832
	ds_read_b128 v[172:175], v166 offset:32896
	ds_read_b128 v[176:179], v166 offset:32960
	ds_read_b32 v146, v158 offset:3072
	ds_read_b64_tr_b16 v[180:181], v159
	ds_read_b64_tr_b16 v[182:183], v159 offset:1088
	ds_read_b64_tr_b16 v[184:185], v159 offset:8704
	ds_read_b64_tr_b16 v[186:187], v159 offset:9792
	s_waitcnt lgkmcnt(2)
	v_mfma_f32_16x16x32_bf16 v[180:183], v[180:183], v[142:145], 0
	s_waitcnt vmcnt(27)
	v_lshlrev_b32_e32 v147, 16, v60
	v_and_b32_e32 v60, 0xffff0000, v60
	s_waitcnt lgkmcnt(0)
	v_mfma_f32_16x16x32_bf16 v[180:183], v[184:187], v[168:171], v[180:183]
	ds_read_b64_tr_b16 v[184:185], v159 offset:17408
	ds_read_b64_tr_b16 v[186:187], v159 offset:18496
	s_waitcnt lgkmcnt(0)
	v_mfma_f32_16x16x32_bf16 v[180:183], v[184:187], v[172:175], v[180:183]
	ds_read_b64_tr_b16 v[184:185], v159 offset:26112
	ds_read_b64_tr_b16 v[186:187], v159 offset:27200
	s_waitcnt lgkmcnt(0)
	v_mfma_f32_16x16x32_bf16 v[180:183], v[184:187], v[176:179], v[180:183]
	s_nop 7
	v_add_f32_e32 v167, v146, v180
	v_mul_f32_e32 v147, v167, v147
	s_waitcnt vmcnt(26)
	v_lshlrev_b32_e32 v167, 16, v56
	v_mul_f32_e32 v147, v147, v167
	v_add_f32_e32 v167, v146, v181
	v_mul_f32_e32 v60, v167, v60
	v_and_b32_e32 v56, 0xffff0000, v56
	v_mul_f32_e32 v56, v60, v56
	v_lshlrev_b32_e32 v60, 16, v61
	v_add_f32_e32 v167, v146, v182
	v_mul_f32_e32 v60, v167, v60
	v_lshlrev_b32_e32 v167, 16, v57
	v_mul_f32_e32 v60, v60, v167
	v_and_b32_e32 v61, 0xffff0000, v61
	v_add_f32_e32 v167, v146, v183
	v_mul_f32_e32 v61, v167, v61
	v_and_b32_e32 v57, 0xffff0000, v57
	v_mul_f32_e32 v57, v61, v57
	v_cvt_pk_bf16_f32 v56, v147, v56
	v_cvt_pk_bf16_f32 v57, v60, v57
	ds_read_b64_tr_b16 v[180:181], v159 offset:8
	ds_read_b64_tr_b16 v[182:183], v159 offset:1096
	ds_read_b64_tr_b16 v[184:185], v159 offset:8712
	ds_read_b64_tr_b16 v[186:187], v159 offset:9800
	s_waitcnt lgkmcnt(2)
	v_mfma_f32_16x16x32_bf16 v[180:183], v[180:183], v[142:145], 0
	v_lshlrev_b32_e32 v60, 16, v62
	s_waitcnt vmcnt(25)
	v_lshlrev_b32_e32 v147, 16, v52
	v_and_b32_e32 v52, 0xffff0000, v52
	s_waitcnt lgkmcnt(0)
	v_mfma_f32_16x16x32_bf16 v[180:183], v[184:187], v[168:171], v[180:183]
	ds_read_b64_tr_b16 v[184:185], v159 offset:17416
	ds_read_b64_tr_b16 v[186:187], v159 offset:18504
	s_waitcnt lgkmcnt(0)
	v_mfma_f32_16x16x32_bf16 v[180:183], v[184:187], v[172:175], v[180:183]
	ds_read_b64_tr_b16 v[184:185], v159 offset:26120
	ds_read_b64_tr_b16 v[186:187], v159 offset:27208
	s_waitcnt lgkmcnt(0)
	v_mfma_f32_16x16x32_bf16 v[180:183], v[184:187], v[176:179], v[180:183]
	s_nop 7
	v_add_f32_e32 v61, v146, v180
	v_mul_f32_e32 v60, v61, v60
	v_lshlrev_b32_e32 v61, 16, v58
	v_mul_f32_e32 v60, v60, v61
	v_and_b32_e32 v61, 0xffff0000, v62
	v_add_f32_e32 v62, v146, v181
	v_mul_f32_e32 v61, v62, v61
	v_and_b32_e32 v58, 0xffff0000, v58
	v_mul_f32_e32 v58, v61, v58
	v_lshlrev_b32_e32 v61, 16, v63
	v_add_f32_e32 v62, v146, v182
	v_mul_f32_e32 v61, v62, v61
	v_lshlrev_b32_e32 v62, 16, v59
	v_mul_f32_e32 v61, v61, v62
	v_and_b32_e32 v62, 0xffff0000, v63
	v_add_f32_e32 v63, v146, v183
	v_mul_f32_e32 v62, v63, v62
	v_and_b32_e32 v59, 0xffff0000, v59
	v_mul_f32_e32 v59, v62, v59
	v_cvt_pk_bf16_f32 v58, v60, v58
	v_cvt_pk_bf16_f32 v59, v61, v59
	ds_read_b64_tr_b16 v[60:61], v159 offset:64
	ds_read_b64_tr_b16 v[62:63], v159 offset:1152
	ds_read_b64_tr_b16 v[180:181], v159 offset:8768
	ds_read_b64_tr_b16 v[182:183], v159 offset:9856
	s_waitcnt lgkmcnt(2)
	v_mfma_f32_16x16x32_bf16 v[60:63], v[60:63], v[142:145], 0
	s_waitcnt lgkmcnt(0)
	v_mfma_f32_16x16x32_bf16 v[60:63], v[180:183], v[168:171], v[60:63]
	ds_read_b64_tr_b16 v[180:181], v159 offset:17472
	ds_read_b64_tr_b16 v[182:183], v159 offset:18560
	s_waitcnt lgkmcnt(0)
	v_mfma_f32_16x16x32_bf16 v[60:63], v[180:183], v[172:175], v[60:63]
	ds_read_b64_tr_b16 v[180:181], v159 offset:26176
	ds_read_b64_tr_b16 v[182:183], v159 offset:27264
	s_waitcnt lgkmcnt(0)
	v_mfma_f32_16x16x32_bf16 v[60:63], v[180:183], v[176:179], v[60:63]
	s_nop 7
	v_add_f32_e32 v60, v146, v60
	v_add_f32_e32 v61, v146, v61
	v_mul_f32_e32 v60, v60, v147
	s_waitcnt vmcnt(24)
	v_lshlrev_b32_e32 v147, 16, v48
	v_mul_f32_e32 v52, v61, v52
	v_and_b32_e32 v48, 0xffff0000, v48
	v_mul_f32_e32 v48, v52, v48
	v_lshlrev_b32_e32 v52, 16, v53
	v_add_f32_e32 v61, v146, v62
	v_mul_f32_e32 v52, v61, v52
	v_lshlrev_b32_e32 v61, 16, v49
	v_mul_f32_e32 v52, v52, v61
	v_and_b32_e32 v53, 0xffff0000, v53
	v_add_f32_e32 v61, v146, v63
	v_mul_f32_e32 v53, v61, v53
	v_and_b32_e32 v49, 0xffff0000, v49
	v_mul_f32_e32 v60, v60, v147
	v_mul_f32_e32 v49, v53, v49
	v_cvt_pk_bf16_f32 v48, v60, v48
	v_cvt_pk_bf16_f32 v49, v52, v49
	ds_read_b64_tr_b16 v[60:61], v159 offset:72
	ds_read_b64_tr_b16 v[62:63], v159 offset:1160
	ds_read_b64_tr_b16 v[180:181], v159 offset:8776
	ds_read_b64_tr_b16 v[182:183], v159 offset:9864
	s_waitcnt lgkmcnt(2)
	v_mfma_f32_16x16x32_bf16 v[60:63], v[60:63], v[142:145], 0
	v_lshlrev_b32_e32 v52, 16, v54
	s_waitcnt lgkmcnt(0)
	v_mfma_f32_16x16x32_bf16 v[60:63], v[180:183], v[168:171], v[60:63]
	ds_read_b64_tr_b16 v[180:181], v159 offset:17480
	ds_read_b64_tr_b16 v[182:183], v159 offset:18568
	s_waitcnt lgkmcnt(0)
	v_mfma_f32_16x16x32_bf16 v[60:63], v[180:183], v[172:175], v[60:63]
	ds_read_b64_tr_b16 v[180:181], v159 offset:26184
	ds_read_b64_tr_b16 v[182:183], v159 offset:27272
	s_waitcnt lgkmcnt(0)
	v_mfma_f32_16x16x32_bf16 v[60:63], v[180:183], v[176:179], v[60:63]
	s_nop 7
	v_add_f32_e32 v53, v146, v60
	v_mul_f32_e32 v52, v53, v52
	v_lshlrev_b32_e32 v53, 16, v50
	v_mul_f32_e32 v52, v52, v53
	v_and_b32_e32 v53, 0xffff0000, v54
	v_add_f32_e32 v54, v146, v61
	v_mul_f32_e32 v53, v54, v53
	v_and_b32_e32 v50, 0xffff0000, v50
	v_mul_f32_e32 v50, v53, v50
	v_lshlrev_b32_e32 v53, 16, v55
	v_add_f32_e32 v54, v146, v62
	v_mul_f32_e32 v53, v54, v53
	v_lshlrev_b32_e32 v54, 16, v51
	v_mul_f32_e32 v53, v53, v54
	v_and_b32_e32 v54, 0xffff0000, v55
	v_add_f32_e32 v55, v146, v63
	v_mul_f32_e32 v54, v55, v54
	v_and_b32_e32 v51, 0xffff0000, v51
	v_mul_f32_e32 v51, v54, v51
	v_cvt_pk_bf16_f32 v50, v52, v50
	v_cvt_pk_bf16_f32 v51, v53, v51
	ds_read_b64_tr_b16 v[52:53], v159 offset:128
	ds_read_b64_tr_b16 v[54:55], v159 offset:1216
	ds_read_b64_tr_b16 v[60:61], v159 offset:8832
	ds_read_b64_tr_b16 v[62:63], v159 offset:9920
	s_waitcnt lgkmcnt(2)
	v_mfma_f32_16x16x32_bf16 v[52:55], v[52:55], v[142:145], 0
	s_waitcnt lgkmcnt(0)
	v_mfma_f32_16x16x32_bf16 v[52:55], v[60:63], v[168:171], v[52:55]
	ds_read_b64_tr_b16 v[60:61], v159 offset:17536
	ds_read_b64_tr_b16 v[62:63], v159 offset:18624
	s_waitcnt lgkmcnt(0)
	v_mfma_f32_16x16x32_bf16 v[52:55], v[60:63], v[172:175], v[52:55]
	ds_read_b64_tr_b16 v[60:61], v159 offset:26240
	ds_read_b64_tr_b16 v[62:63], v159 offset:27328
	s_waitcnt lgkmcnt(0)
	v_mfma_f32_16x16x32_bf16 v[52:55], v[60:63], v[176:179], v[52:55]
	s_waitcnt vmcnt(23)
	v_lshlrev_b32_e32 v60, 16, v44
	v_and_b32_e32 v44, 0xffff0000, v44
	s_nop 4
	v_add_f32_e32 v52, v146, v52
	v_add_f32_e32 v53, v146, v53
	v_mul_f32_e32 v52, v52, v60
	s_waitcnt vmcnt(22)
	v_lshlrev_b32_e32 v60, 16, v40
	v_mul_f32_e32 v44, v53, v44
	v_and_b32_e32 v40, 0xffff0000, v40
	v_mul_f32_e32 v40, v44, v40
	v_lshlrev_b32_e32 v44, 16, v45
	v_add_f32_e32 v53, v146, v54
	v_mul_f32_e32 v44, v53, v44
	v_lshlrev_b32_e32 v53, 16, v41
	v_mul_f32_e32 v44, v44, v53
	v_and_b32_e32 v45, 0xffff0000, v45
	v_add_f32_e32 v53, v146, v55
	v_mul_f32_e32 v45, v53, v45
	v_and_b32_e32 v41, 0xffff0000, v41
	v_mul_f32_e32 v52, v52, v60
	v_mul_f32_e32 v41, v45, v41
	v_cvt_pk_bf16_f32 v40, v52, v40
	v_cvt_pk_bf16_f32 v41, v44, v41
	ds_read_b64_tr_b16 v[52:53], v159 offset:136
	ds_read_b64_tr_b16 v[54:55], v159 offset:1224
	ds_read_b64_tr_b16 v[60:61], v159 offset:8840
	ds_read_b64_tr_b16 v[62:63], v159 offset:9928
	s_waitcnt lgkmcnt(2)
	v_mfma_f32_16x16x32_bf16 v[52:55], v[52:55], v[142:145], 0
	v_lshlrev_b32_e32 v44, 16, v46
	s_waitcnt lgkmcnt(0)
	v_mfma_f32_16x16x32_bf16 v[52:55], v[60:63], v[168:171], v[52:55]
	ds_read_b64_tr_b16 v[60:61], v159 offset:17544
	ds_read_b64_tr_b16 v[62:63], v159 offset:18632
	s_waitcnt lgkmcnt(0)
	v_mfma_f32_16x16x32_bf16 v[52:55], v[60:63], v[172:175], v[52:55]
	ds_read_b64_tr_b16 v[60:61], v159 offset:26248
	ds_read_b64_tr_b16 v[62:63], v159 offset:27336
	s_waitcnt lgkmcnt(0)
	v_mfma_f32_16x16x32_bf16 v[52:55], v[60:63], v[176:179], v[52:55]
	s_waitcnt vmcnt(12)
	v_and_b32_e32 v61, 0xffff0000, v74
	v_lshlrev_b32_e32 v60, 16, v74
	v_and_b32_e32 v63, 0xffff0000, v75
	s_nop 3
	v_add_f32_e32 v45, v146, v52
	v_mul_f32_e32 v44, v45, v44
	v_lshlrev_b32_e32 v45, 16, v42
	v_mul_f32_e32 v44, v44, v45
	v_and_b32_e32 v45, 0xffff0000, v46
	v_add_f32_e32 v46, v146, v53
	v_mul_f32_e32 v45, v46, v45
	v_and_b32_e32 v42, 0xffff0000, v42
	v_mul_f32_e32 v42, v45, v42
	v_lshlrev_b32_e32 v45, 16, v47
	v_add_f32_e32 v46, v146, v54
	v_mul_f32_e32 v45, v46, v45
	v_lshlrev_b32_e32 v46, 16, v43
	v_mul_f32_e32 v45, v45, v46
	v_and_b32_e32 v46, 0xffff0000, v47
	v_add_f32_e32 v47, v146, v55
	v_mul_f32_e32 v46, v47, v46
	v_and_b32_e32 v43, 0xffff0000, v43
	v_mul_f32_e32 v43, v46, v43
	v_cvt_pk_bf16_f32 v42, v44, v42
	v_cvt_pk_bf16_f32 v43, v45, v43
	ds_read_b64_tr_b16 v[44:45], v159 offset:192
	ds_read_b64_tr_b16 v[46:47], v159 offset:1280
	ds_read_b64_tr_b16 v[52:53], v159 offset:8896
	ds_read_b64_tr_b16 v[54:55], v159 offset:9984
	s_waitcnt lgkmcnt(2)
	v_mfma_f32_16x16x32_bf16 v[44:47], v[44:47], v[142:145], 0
	v_lshlrev_b32_e32 v62, 16, v75
	v_lshlrev_b32_e32 v74, 16, v70
	v_and_b32_e32 v70, 0xffff0000, v70
	s_waitcnt lgkmcnt(0)
	v_mfma_f32_16x16x32_bf16 v[44:47], v[52:55], v[168:171], v[44:47]
	ds_read_b64_tr_b16 v[52:53], v159 offset:17600
	ds_read_b64_tr_b16 v[54:55], v159 offset:18688
	v_lshlrev_b32_e32 v75, 16, v71
	v_and_b32_e32 v71, 0xffff0000, v71
	s_waitcnt lgkmcnt(0)
	v_mfma_f32_16x16x32_bf16 v[44:47], v[52:55], v[172:175], v[44:47]
	ds_read_b64_tr_b16 v[52:53], v159 offset:26304
	ds_read_b64_tr_b16 v[54:55], v159 offset:27392
	s_waitcnt lgkmcnt(0)
	v_mfma_f32_16x16x32_bf16 v[44:47], v[52:55], v[176:179], v[44:47]
	v_lshlrev_b32_e32 v52, 16, v36
	v_and_b32_e32 v36, 0xffff0000, v36
	s_nop 5
	v_add_f32_e32 v44, v146, v44
	v_add_f32_e32 v45, v146, v45
	v_mul_f32_e32 v44, v44, v52
	v_lshlrev_b32_e32 v52, 16, v32
	v_mul_f32_e32 v36, v45, v36
	v_and_b32_e32 v32, 0xffff0000, v32
	v_mul_f32_e32 v32, v36, v32
	v_lshlrev_b32_e32 v36, 16, v37
	v_add_f32_e32 v45, v146, v46
	v_mul_f32_e32 v36, v45, v36
	v_lshlrev_b32_e32 v45, 16, v33
	v_mul_f32_e32 v36, v36, v45
	v_and_b32_e32 v37, 0xffff0000, v37
	v_add_f32_e32 v45, v146, v47
	v_mul_f32_e32 v37, v45, v37
	v_and_b32_e32 v33, 0xffff0000, v33
	v_mul_f32_e32 v44, v44, v52
	v_mul_f32_e32 v33, v37, v33
	v_cvt_pk_bf16_f32 v32, v44, v32
	v_cvt_pk_bf16_f32 v33, v36, v33
	ds_read_b64_tr_b16 v[44:45], v159 offset:200
	ds_read_b64_tr_b16 v[46:47], v159 offset:1288
	ds_read_b64_tr_b16 v[52:53], v159 offset:8904
	ds_read_b64_tr_b16 v[54:55], v159 offset:9992
	s_waitcnt lgkmcnt(2)
	v_mfma_f32_16x16x32_bf16 v[44:47], v[44:47], v[142:145], 0
	v_lshlrev_b32_e32 v36, 16, v38
	s_waitcnt lgkmcnt(0)
	v_mfma_f32_16x16x32_bf16 v[44:47], v[52:55], v[168:171], v[44:47]
	ds_read_b64_tr_b16 v[52:53], v159 offset:17608
	ds_read_b64_tr_b16 v[54:55], v159 offset:18696
	s_waitcnt lgkmcnt(0)
	v_mfma_f32_16x16x32_bf16 v[44:47], v[52:55], v[172:175], v[44:47]
	ds_read_b64_tr_b16 v[52:53], v159 offset:26312
	ds_read_b64_tr_b16 v[54:55], v159 offset:27400
	s_waitcnt lgkmcnt(0)
	v_mfma_f32_16x16x32_bf16 v[44:47], v[52:55], v[176:179], v[44:47]
	s_waitcnt vmcnt(11)
	v_and_b32_e32 v53, 0xffff0000, v78
	v_lshlrev_b32_e32 v52, 16, v78
	v_and_b32_e32 v55, 0xffff0000, v79
	s_nop 3
	v_add_f32_e32 v37, v146, v44
	v_mul_f32_e32 v36, v37, v36
	v_lshlrev_b32_e32 v37, 16, v34
	v_mul_f32_e32 v36, v36, v37
	v_and_b32_e32 v37, 0xffff0000, v38
	v_add_f32_e32 v38, v146, v45
	v_mul_f32_e32 v37, v38, v37
	v_and_b32_e32 v34, 0xffff0000, v34
	v_mul_f32_e32 v34, v37, v34
	v_lshlrev_b32_e32 v37, 16, v39
	v_add_f32_e32 v38, v146, v46
	v_mul_f32_e32 v37, v38, v37
	v_lshlrev_b32_e32 v38, 16, v35
	v_mul_f32_e32 v37, v37, v38
	v_and_b32_e32 v38, 0xffff0000, v39
	v_add_f32_e32 v39, v146, v47
	v_mul_f32_e32 v38, v39, v38
	v_and_b32_e32 v35, 0xffff0000, v35
	v_mul_f32_e32 v35, v38, v35
	v_cvt_pk_bf16_f32 v34, v36, v34
	v_cvt_pk_bf16_f32 v35, v37, v35
	global_store_dwordx4 v[148:149], v[56:59], off offset:512
	global_store_dwordx4 v[148:149], v[48:51], off offset:576
	global_store_dwordx4 v[148:149], v[40:43], off offset:640
	global_store_dwordx4 v[148:149], v[32:35], off offset:704
	v_and_b32_e32 v49, 0xffff0000, v76
	v_and_b32_e32 v51, 0xffff0000, v77
	v_lshlrev_b32_e32 v48, 16, v76
	v_mul_f32_e32 v32, v49, v49
	v_lshlrev_b32_e32 v50, 16, v77
	v_mul_f32_e32 v33, v51, v51
	v_fmac_f32_e32 v32, v48, v48
	v_fmac_f32_e32 v33, v50, v50
	v_add_f32_e32 v32, v32, v33
	v_mul_f32_e32 v33, v53, v53
	v_fmac_f32_e32 v33, v52, v52
	v_add_f32_e32 v32, v33, v32
	v_lshlrev_b32_e32 v54, 16, v79
	v_mul_f32_e32 v33, v55, v55
	v_fmac_f32_e32 v33, v54, v54
	v_and_b32_e32 v57, 0xffff0000, v72
	v_add_f32_e32 v32, v33, v32
	v_lshlrev_b32_e32 v56, 16, v72
	v_mul_f32_e32 v33, v57, v57
	v_fmac_f32_e32 v33, v56, v56
	v_and_b32_e32 v59, 0xffff0000, v73
	v_add_f32_e32 v32, v33, v32
	v_lshlrev_b32_e32 v58, 16, v73
	v_mul_f32_e32 v33, v59, v59
	v_fmac_f32_e32 v33, v58, v58
	v_add_f32_e32 v32, v33, v32
	v_mul_f32_e32 v33, v61, v61
	v_fmac_f32_e32 v33, v60, v60
	v_add_f32_e32 v32, v33, v32
	v_mul_f32_e32 v33, v63, v63
	v_fmac_f32_e32 v33, v62, v62
	v_lshlrev_b32_e32 v72, 16, v68
	v_and_b32_e32 v68, 0xffff0000, v68
	v_add_f32_e32 v32, v33, v32
	v_mul_f32_e32 v33, v68, v68
	v_fmac_f32_e32 v33, v72, v72
	v_lshlrev_b32_e32 v73, 16, v69
	v_and_b32_e32 v69, 0xffff0000, v69
	v_add_f32_e32 v32, v33, v32
	v_mul_f32_e32 v33, v69, v69
	v_fmac_f32_e32 v33, v73, v73
	v_add_f32_e32 v32, v33, v32
	v_mul_f32_e32 v33, v70, v70
	v_fmac_f32_e32 v33, v74, v74
	v_add_f32_e32 v32, v33, v32
	v_mul_f32_e32 v33, v71, v71
	v_fmac_f32_e32 v33, v75, v75
	v_and_b32_e32 v43, 0xffff0000, v65
	v_and_b32_e32 v42, 0xffff0000, v64
	v_add_f32_e32 v34, v33, v32
	v_lshlrev_b32_e32 v41, 16, v65
	v_lshlrev_b32_e32 v40, 16, v64
	v_pk_mul_f32 v[32:33], v[42:43], v[42:43]
	v_and_b32_e32 v47, 0xffff0000, v67
	v_pk_fma_f32 v[32:33], v[40:41], v[40:41], v[32:33]
	v_and_b32_e32 v46, 0xffff0000, v66
	v_add_f32_e32 v32, v32, v34
	v_add_f32_e32 v34, v33, v32
	v_lshlrev_b32_e32 v45, 16, v67
	v_lshlrev_b32_e32 v44, 16, v66
	v_pk_mul_f32 v[32:33], v[46:47], v[46:47]
	s_nop 0
	v_pk_fma_f32 v[32:33], v[44:45], v[44:45], v[32:33]
	s_barrier
	v_add_f32_e32 v32, v32, v34
	v_add_f32_e32 v32, v33, v32
	ds_bpermute_b32 v33, v155, v32
	s_waitcnt lgkmcnt(0)
	ds_write_b128 v160, v[80:83] offset:32768
	s_waitcnt vmcnt(14)
	ds_write_b128 v161, v[84:87] offset:32768
	s_waitcnt vmcnt(13)
	ds_write_b128 v162, v[88:91] offset:32768
	s_waitcnt vmcnt(12)
	ds_write_b128 v163, v[92:95] offset:32768
	v_add_f32_e32 v32, v32, v33
	ds_bpermute_b32 v33, v156, v32
	s_waitcnt lgkmcnt(0)
	v_add_f32_e32 v32, v32, v33
	v_fmamk_f32 v32, v32, 0x3c000000, v164
	v_rsq_f32_e32 v64, v32
	ds_read_b128 v[32:35], v157 offset:1536
	ds_read_b128 v[36:39], v157 offset:1552
	v_mul_f32_e32 v48, v64, v48
	s_waitcnt lgkmcnt(1)
	v_mul_f32_e32 v32, v32, v48
	v_mul_f32_e32 v48, v64, v49
	v_mul_f32_e32 v33, v33, v48
	v_cvt_pk_bf16_f32 v32, v32, v33
	v_mul_f32_e32 v33, v64, v50
	v_mul_f32_e32 v33, v34, v33
	v_mul_f32_e32 v34, v64, v51
	v_mul_f32_e32 v34, v35, v34
	v_cvt_pk_bf16_f32 v33, v33, v34
	v_mul_f32_e32 v34, v64, v52
	v_mul_f32_e32 v35, v64, v53
	s_waitcnt lgkmcnt(0)
	v_mul_f32_e32 v34, v36, v34
	v_mul_f32_e32 v35, v37, v35
	v_cvt_pk_bf16_f32 v34, v34, v35
	v_mul_f32_e32 v35, v64, v54
	v_mul_f32_e32 v35, v38, v35
	v_mul_f32_e32 v36, v64, v55
	v_mul_f32_e32 v36, v39, v36
	v_cvt_pk_bf16_f32 v35, v35, v36
	ds_write_b128 v165, v[32:35]
	ds_read_b128 v[32:35], v157 offset:1568
	ds_read_b128 v[36:39], v157 offset:1584
	v_mul_f32_e32 v48, v64, v56
	v_mul_f32_e32 v40, v64, v40
	s_waitcnt lgkmcnt(1)
	v_mul_f32_e32 v32, v48, v32
	v_mul_f32_e32 v48, v64, v57
	v_mul_f32_e32 v33, v48, v33
	v_cvt_pk_bf16_f32 v32, v32, v33
	v_mul_f32_e32 v33, v64, v58
	v_mul_f32_e32 v33, v33, v34
	v_mul_f32_e32 v34, v64, v59
	v_mul_f32_e32 v34, v34, v35
	v_cvt_pk_bf16_f32 v33, v33, v34
	v_mul_f32_e32 v34, v64, v60
	v_mul_f32_e32 v35, v64, v61
	s_waitcnt lgkmcnt(0)
	v_mul_f32_e32 v34, v34, v36
	v_mul_f32_e32 v35, v35, v37
	v_cvt_pk_bf16_f32 v34, v34, v35
	v_mul_f32_e32 v35, v64, v62
	v_mul_f32_e32 v35, v35, v38
	v_mul_f32_e32 v36, v64, v63
	v_mul_f32_e32 v36, v36, v39
	v_cvt_pk_bf16_f32 v35, v35, v36
	ds_write_b128 v165, v[32:35] offset:16
	ds_read_b128 v[32:35], v157 offset:1600
	ds_read_b128 v[36:39], v157 offset:1616
	v_mul_f32_e32 v48, v64, v72
	s_waitcnt lgkmcnt(1)
	v_mul_f32_e32 v32, v48, v32
	v_mul_f32_e32 v48, v64, v68
	v_mul_f32_e32 v33, v48, v33
	v_cvt_pk_bf16_f32 v32, v32, v33
	v_mul_f32_e32 v33, v64, v73
	v_mul_f32_e32 v33, v33, v34
	v_mul_f32_e32 v34, v64, v69
	v_mul_f32_e32 v34, v34, v35
	v_cvt_pk_bf16_f32 v33, v33, v34
	v_mul_f32_e32 v34, v64, v74
	v_mul_f32_e32 v35, v64, v70
	s_waitcnt lgkmcnt(0)
	v_mul_f32_e32 v34, v34, v36
	v_mul_f32_e32 v35, v35, v37
	v_cvt_pk_bf16_f32 v34, v34, v35
	v_mul_f32_e32 v35, v64, v75
	v_mul_f32_e32 v35, v35, v38
	v_mul_f32_e32 v36, v64, v71
	v_mul_f32_e32 v36, v36, v39
	v_cvt_pk_bf16_f32 v35, v35, v36
	ds_write_b128 v165, v[32:35] offset:32
	ds_read_b128 v[32:35], v157 offset:1632
	ds_read_b128 v[36:39], v157 offset:1648
	s_waitcnt lgkmcnt(1)
	v_mul_f32_e32 v32, v40, v32
	v_mul_f32_e32 v40, v64, v42
	v_mul_f32_e32 v33, v40, v33
	v_cvt_pk_bf16_f32 v32, v32, v33
	v_mul_f32_e32 v33, v64, v41
	v_mul_f32_e32 v33, v33, v34
	v_mul_f32_e32 v34, v64, v43
	v_mul_f32_e32 v34, v34, v35
	v_cvt_pk_bf16_f32 v33, v33, v34
	v_mul_f32_e32 v34, v64, v44
	v_mul_f32_e32 v35, v64, v46
	s_waitcnt lgkmcnt(0)
	v_mul_f32_e32 v34, v34, v36
	v_mul_f32_e32 v35, v35, v37
	v_cvt_pk_bf16_f32 v34, v34, v35
	v_mul_f32_e32 v35, v64, v45
	v_mul_f32_e32 v35, v35, v38
	v_mul_f32_e32 v36, v64, v47
	v_mul_f32_e32 v36, v36, v39
	v_cvt_pk_bf16_f32 v35, v35, v36
	ds_write_b128 v165, v[32:35] offset:48
	s_waitcnt lgkmcnt(0)
	s_barrier
	ds_read_b128 v[32:35], v166 offset:32768
	ds_read_b128 v[36:39], v166 offset:32832
	ds_read_b128 v[40:43], v166 offset:32896
	ds_read_b128 v[44:47], v166 offset:32960
	ds_read_b32 v56, v158 offset:3584
	ds_read_b64_tr_b16 v[48:49], v159
	ds_read_b64_tr_b16 v[50:51], v159 offset:1088
	ds_read_b64_tr_b16 v[52:53], v159 offset:8704
	ds_read_b64_tr_b16 v[54:55], v159 offset:9792
	s_waitcnt lgkmcnt(2)
	v_mfma_f32_16x16x32_bf16 v[48:51], v[48:51], v[32:35], 0
	s_waitcnt lgkmcnt(0)
	v_mfma_f32_16x16x32_bf16 v[48:51], v[52:55], v[36:39], v[48:51]
	ds_read_b64_tr_b16 v[52:53], v159 offset:17408
	ds_read_b64_tr_b16 v[54:55], v159 offset:18496
	s_waitcnt lgkmcnt(0)
	v_mfma_f32_16x16x32_bf16 v[48:51], v[52:55], v[40:43], v[48:51]
	ds_read_b64_tr_b16 v[52:53], v159 offset:26112
	ds_read_b64_tr_b16 v[54:55], v159 offset:27200
	s_waitcnt lgkmcnt(0)
	v_mfma_f32_16x16x32_bf16 v[48:51], v[52:55], v[44:47], v[48:51]
	s_waitcnt vmcnt(11)
	v_lshlrev_b32_e32 v52, 16, v28
	v_and_b32_e32 v28, 0xffff0000, v28
	s_nop 4
	v_add_f32_e32 v48, v56, v48
	v_add_f32_e32 v49, v56, v49
	v_mul_f32_e32 v48, v48, v52
	s_waitcnt vmcnt(10)
	v_lshlrev_b32_e32 v52, 16, v24
	v_mul_f32_e32 v28, v49, v28
	v_and_b32_e32 v24, 0xffff0000, v24
	v_mul_f32_e32 v24, v28, v24
	v_lshlrev_b32_e32 v28, 16, v29
	v_add_f32_e32 v49, v56, v50
	v_mul_f32_e32 v28, v49, v28
	v_lshlrev_b32_e32 v49, 16, v25
	v_mul_f32_e32 v28, v28, v49
	v_and_b32_e32 v29, 0xffff0000, v29
	v_add_f32_e32 v49, v56, v51
	v_mul_f32_e32 v29, v49, v29
	v_and_b32_e32 v25, 0xffff0000, v25
	v_mul_f32_e32 v48, v48, v52
	v_mul_f32_e32 v25, v29, v25
	v_cvt_pk_bf16_f32 v24, v48, v24
	v_cvt_pk_bf16_f32 v25, v28, v25
	ds_read_b64_tr_b16 v[48:49], v159 offset:8
	ds_read_b64_tr_b16 v[50:51], v159 offset:1096
	ds_read_b64_tr_b16 v[52:53], v159 offset:8712
	ds_read_b64_tr_b16 v[54:55], v159 offset:9800
	s_waitcnt lgkmcnt(2)
	v_mfma_f32_16x16x32_bf16 v[48:51], v[48:51], v[32:35], 0
	v_lshlrev_b32_e32 v28, 16, v30
	s_waitcnt lgkmcnt(0)
	v_mfma_f32_16x16x32_bf16 v[48:51], v[52:55], v[36:39], v[48:51]
	ds_read_b64_tr_b16 v[52:53], v159 offset:17416
	ds_read_b64_tr_b16 v[54:55], v159 offset:18504
	s_waitcnt lgkmcnt(0)
	v_mfma_f32_16x16x32_bf16 v[48:51], v[52:55], v[40:43], v[48:51]
	ds_read_b64_tr_b16 v[52:53], v159 offset:26120
	ds_read_b64_tr_b16 v[54:55], v159 offset:27208
	s_waitcnt lgkmcnt(0)
	v_mfma_f32_16x16x32_bf16 v[48:51], v[52:55], v[44:47], v[48:51]
	s_nop 7
	v_add_f32_e32 v29, v56, v48
	v_mul_f32_e32 v28, v29, v28
	v_lshlrev_b32_e32 v29, 16, v26
	v_mul_f32_e32 v28, v28, v29
	v_and_b32_e32 v29, 0xffff0000, v30
	v_add_f32_e32 v30, v56, v49
	v_mul_f32_e32 v29, v30, v29
	v_and_b32_e32 v26, 0xffff0000, v26
	v_mul_f32_e32 v26, v29, v26
	v_lshlrev_b32_e32 v29, 16, v31
	v_add_f32_e32 v30, v56, v50
	v_mul_f32_e32 v29, v30, v29
	v_lshlrev_b32_e32 v30, 16, v27
	v_mul_f32_e32 v29, v29, v30
	v_and_b32_e32 v30, 0xffff0000, v31
	v_add_f32_e32 v31, v56, v51
	v_mul_f32_e32 v30, v31, v30
	v_and_b32_e32 v27, 0xffff0000, v27
	v_mul_f32_e32 v27, v30, v27
	v_cvt_pk_bf16_f32 v26, v28, v26
	v_cvt_pk_bf16_f32 v27, v29, v27
	ds_read_b64_tr_b16 v[28:29], v159 offset:64
	ds_read_b64_tr_b16 v[30:31], v159 offset:1152
	ds_read_b64_tr_b16 v[48:49], v159 offset:8768
	ds_read_b64_tr_b16 v[50:51], v159 offset:9856
	s_waitcnt lgkmcnt(2)
	v_mfma_f32_16x16x32_bf16 v[28:31], v[28:31], v[32:35], 0
	s_waitcnt lgkmcnt(0)
	v_mfma_f32_16x16x32_bf16 v[28:31], v[48:51], v[36:39], v[28:31]
	ds_read_b64_tr_b16 v[48:49], v159 offset:17472
	ds_read_b64_tr_b16 v[50:51], v159 offset:18560
	s_waitcnt lgkmcnt(0)
	v_mfma_f32_16x16x32_bf16 v[28:31], v[48:51], v[40:43], v[28:31]
	ds_read_b64_tr_b16 v[48:49], v159 offset:26176
	ds_read_b64_tr_b16 v[50:51], v159 offset:27264
	s_waitcnt lgkmcnt(0)
	v_mfma_f32_16x16x32_bf16 v[28:31], v[48:51], v[44:47], v[28:31]
	s_waitcnt vmcnt(9)
	v_lshlrev_b32_e32 v48, 16, v20
	v_and_b32_e32 v20, 0xffff0000, v20
	s_nop 4
	v_add_f32_e32 v28, v56, v28
	v_add_f32_e32 v29, v56, v29
	v_mul_f32_e32 v28, v28, v48
	s_waitcnt vmcnt(8)
	v_lshlrev_b32_e32 v48, 16, v16
	v_mul_f32_e32 v20, v29, v20
	v_and_b32_e32 v16, 0xffff0000, v16
	v_mul_f32_e32 v16, v20, v16
	v_lshlrev_b32_e32 v20, 16, v21
	v_add_f32_e32 v29, v56, v30
	v_mul_f32_e32 v20, v29, v20
	v_lshlrev_b32_e32 v29, 16, v17
	v_mul_f32_e32 v20, v20, v29
	v_and_b32_e32 v21, 0xffff0000, v21
	v_add_f32_e32 v29, v56, v31
	v_mul_f32_e32 v21, v29, v21
	v_and_b32_e32 v17, 0xffff0000, v17
	v_mul_f32_e32 v28, v28, v48
	v_mul_f32_e32 v17, v21, v17
	v_cvt_pk_bf16_f32 v16, v28, v16
	v_cvt_pk_bf16_f32 v17, v20, v17
	ds_read_b64_tr_b16 v[28:29], v159 offset:72
	ds_read_b64_tr_b16 v[30:31], v159 offset:1160
	ds_read_b64_tr_b16 v[48:49], v159 offset:8776
	ds_read_b64_tr_b16 v[50:51], v159 offset:9864
	s_waitcnt lgkmcnt(2)
	v_mfma_f32_16x16x32_bf16 v[28:31], v[28:31], v[32:35], 0
	v_lshlrev_b32_e32 v20, 16, v22
	s_waitcnt lgkmcnt(0)
	v_mfma_f32_16x16x32_bf16 v[28:31], v[48:51], v[36:39], v[28:31]
	ds_read_b64_tr_b16 v[48:49], v159 offset:17480
	ds_read_b64_tr_b16 v[50:51], v159 offset:18568
	s_waitcnt lgkmcnt(0)
	v_mfma_f32_16x16x32_bf16 v[28:31], v[48:51], v[40:43], v[28:31]
	ds_read_b64_tr_b16 v[48:49], v159 offset:26184
	ds_read_b64_tr_b16 v[50:51], v159 offset:27272
	s_waitcnt lgkmcnt(0)
	v_mfma_f32_16x16x32_bf16 v[28:31], v[48:51], v[44:47], v[28:31]
	s_nop 7
	v_add_f32_e32 v21, v56, v28
	v_mul_f32_e32 v20, v21, v20
	v_lshlrev_b32_e32 v21, 16, v18
	v_mul_f32_e32 v20, v20, v21
	v_and_b32_e32 v21, 0xffff0000, v22
	v_add_f32_e32 v22, v56, v29
	v_mul_f32_e32 v21, v22, v21
	v_and_b32_e32 v18, 0xffff0000, v18
	v_mul_f32_e32 v18, v21, v18
	v_lshlrev_b32_e32 v21, 16, v23
	v_add_f32_e32 v22, v56, v30
	v_mul_f32_e32 v21, v22, v21
	v_lshlrev_b32_e32 v22, 16, v19
	v_mul_f32_e32 v21, v21, v22
	v_and_b32_e32 v22, 0xffff0000, v23
	v_add_f32_e32 v23, v56, v31
	v_mul_f32_e32 v22, v23, v22
	v_and_b32_e32 v19, 0xffff0000, v19
	v_mul_f32_e32 v19, v22, v19
	v_cvt_pk_bf16_f32 v18, v20, v18
	v_cvt_pk_bf16_f32 v19, v21, v19
	ds_read_b64_tr_b16 v[20:21], v159 offset:128
	ds_read_b64_tr_b16 v[22:23], v159 offset:1216
	ds_read_b64_tr_b16 v[28:29], v159 offset:8832
	ds_read_b64_tr_b16 v[30:31], v159 offset:9920
	s_waitcnt lgkmcnt(2)
	v_mfma_f32_16x16x32_bf16 v[20:23], v[20:23], v[32:35], 0
	s_waitcnt lgkmcnt(0)
	v_mfma_f32_16x16x32_bf16 v[20:23], v[28:31], v[36:39], v[20:23]
	ds_read_b64_tr_b16 v[28:29], v159 offset:17536
	ds_read_b64_tr_b16 v[30:31], v159 offset:18624
	s_waitcnt lgkmcnt(0)
	v_mfma_f32_16x16x32_bf16 v[20:23], v[28:31], v[40:43], v[20:23]
	ds_read_b64_tr_b16 v[28:29], v159 offset:26240
	ds_read_b64_tr_b16 v[30:31], v159 offset:27328
	s_waitcnt lgkmcnt(0)
	v_mfma_f32_16x16x32_bf16 v[20:23], v[28:31], v[44:47], v[20:23]
	s_waitcnt vmcnt(7)
	v_lshlrev_b32_e32 v28, 16, v12
	v_and_b32_e32 v12, 0xffff0000, v12
	s_nop 4
	v_add_f32_e32 v20, v56, v20
	v_add_f32_e32 v21, v56, v21
	v_mul_f32_e32 v20, v20, v28
	s_waitcnt vmcnt(6)
	v_lshlrev_b32_e32 v28, 16, v8
	v_mul_f32_e32 v12, v21, v12
	v_and_b32_e32 v8, 0xffff0000, v8
	v_mul_f32_e32 v8, v12, v8
	v_lshlrev_b32_e32 v12, 16, v13
	v_add_f32_e32 v21, v56, v22
	v_mul_f32_e32 v12, v21, v12
	v_lshlrev_b32_e32 v21, 16, v9
	v_mul_f32_e32 v12, v12, v21
	v_and_b32_e32 v13, 0xffff0000, v13
	v_add_f32_e32 v21, v56, v23
	v_mul_f32_e32 v13, v21, v13
	v_and_b32_e32 v9, 0xffff0000, v9
	v_mul_f32_e32 v20, v20, v28
	v_mul_f32_e32 v9, v13, v9
	v_cvt_pk_bf16_f32 v8, v20, v8
	v_cvt_pk_bf16_f32 v9, v12, v9
	ds_read_b64_tr_b16 v[20:21], v159 offset:136
	ds_read_b64_tr_b16 v[22:23], v159 offset:1224
	ds_read_b64_tr_b16 v[28:29], v159 offset:8840
	ds_read_b64_tr_b16 v[30:31], v159 offset:9928
	s_waitcnt lgkmcnt(2)
	v_mfma_f32_16x16x32_bf16 v[20:23], v[20:23], v[32:35], 0
	v_lshlrev_b32_e32 v12, 16, v14
	s_waitcnt lgkmcnt(0)
	v_mfma_f32_16x16x32_bf16 v[20:23], v[28:31], v[36:39], v[20:23]
	ds_read_b64_tr_b16 v[28:29], v159 offset:17544
	ds_read_b64_tr_b16 v[30:31], v159 offset:18632
	s_waitcnt lgkmcnt(0)
	v_mfma_f32_16x16x32_bf16 v[20:23], v[28:31], v[40:43], v[20:23]
	ds_read_b64_tr_b16 v[28:29], v159 offset:26248
	ds_read_b64_tr_b16 v[30:31], v159 offset:27336
	s_waitcnt lgkmcnt(0)
	v_mfma_f32_16x16x32_bf16 v[20:23], v[28:31], v[44:47], v[20:23]
	s_nop 7
	v_add_f32_e32 v13, v56, v20
	v_mul_f32_e32 v12, v13, v12
	v_lshlrev_b32_e32 v13, 16, v10
	v_mul_f32_e32 v12, v12, v13
	v_and_b32_e32 v13, 0xffff0000, v14
	v_add_f32_e32 v14, v56, v21
	v_mul_f32_e32 v13, v14, v13
	v_and_b32_e32 v10, 0xffff0000, v10
	v_mul_f32_e32 v10, v13, v10
	v_lshlrev_b32_e32 v13, 16, v15
	v_add_f32_e32 v14, v56, v22
	v_mul_f32_e32 v13, v14, v13
	v_lshlrev_b32_e32 v14, 16, v11
	v_mul_f32_e32 v13, v13, v14
	v_and_b32_e32 v14, 0xffff0000, v15
	v_add_f32_e32 v15, v56, v23
	v_mul_f32_e32 v14, v15, v14
	v_and_b32_e32 v11, 0xffff0000, v11
	v_mul_f32_e32 v11, v14, v11
	v_cvt_pk_bf16_f32 v10, v12, v10
	v_cvt_pk_bf16_f32 v11, v13, v11
	ds_read_b64_tr_b16 v[12:13], v159 offset:192
	ds_read_b64_tr_b16 v[14:15], v159 offset:1280
	ds_read_b64_tr_b16 v[20:21], v159 offset:8896
	ds_read_b64_tr_b16 v[22:23], v159 offset:9984
	s_waitcnt lgkmcnt(2)
	v_mfma_f32_16x16x32_bf16 v[12:15], v[12:15], v[32:35], 0
	s_waitcnt lgkmcnt(0)
	v_mfma_f32_16x16x32_bf16 v[12:15], v[20:23], v[36:39], v[12:15]
	ds_read_b64_tr_b16 v[20:21], v159 offset:17600
	ds_read_b64_tr_b16 v[22:23], v159 offset:18688
	s_waitcnt lgkmcnt(0)
	v_mfma_f32_16x16x32_bf16 v[12:15], v[20:23], v[40:43], v[12:15]
	ds_read_b64_tr_b16 v[20:21], v159 offset:26304
	ds_read_b64_tr_b16 v[22:23], v159 offset:27392
	s_waitcnt lgkmcnt(0)
	v_mfma_f32_16x16x32_bf16 v[12:15], v[20:23], v[44:47], v[12:15]
	s_waitcnt vmcnt(5)
	v_lshlrev_b32_e32 v20, 16, v4
	v_and_b32_e32 v4, 0xffff0000, v4
	s_nop 4
	v_add_f32_e32 v12, v56, v12
	v_add_f32_e32 v13, v56, v13
	v_mul_f32_e32 v12, v12, v20
	s_waitcnt vmcnt(4)
	v_lshlrev_b32_e32 v20, 16, v0
	v_mul_f32_e32 v4, v13, v4
	v_and_b32_e32 v0, 0xffff0000, v0
	v_mul_f32_e32 v0, v4, v0
	v_lshlrev_b32_e32 v4, 16, v5
	v_add_f32_e32 v13, v56, v14
	v_mul_f32_e32 v4, v13, v4
	v_lshlrev_b32_e32 v13, 16, v1
	v_mul_f32_e32 v4, v4, v13
	v_and_b32_e32 v5, 0xffff0000, v5
	v_add_f32_e32 v13, v56, v15
	v_mul_f32_e32 v5, v13, v5
	v_and_b32_e32 v1, 0xffff0000, v1
	v_mul_f32_e32 v12, v12, v20
	v_mul_f32_e32 v1, v5, v1
	v_cvt_pk_bf16_f32 v0, v12, v0
	v_cvt_pk_bf16_f32 v1, v4, v1
	ds_read_b64_tr_b16 v[12:13], v159 offset:200
	ds_read_b64_tr_b16 v[14:15], v159 offset:1288
	ds_read_b64_tr_b16 v[20:21], v159 offset:8904
	ds_read_b64_tr_b16 v[22:23], v159 offset:9992
	s_waitcnt lgkmcnt(2)
	v_mfma_f32_16x16x32_bf16 v[12:15], v[12:15], v[32:35], 0
	v_lshlrev_b32_e32 v4, 16, v6
	s_waitcnt lgkmcnt(0)
	v_mfma_f32_16x16x32_bf16 v[12:15], v[20:23], v[36:39], v[12:15]
	ds_read_b64_tr_b16 v[20:21], v159 offset:17608
	ds_read_b64_tr_b16 v[22:23], v159 offset:18696
	s_waitcnt lgkmcnt(0)
	v_mfma_f32_16x16x32_bf16 v[12:15], v[20:23], v[40:43], v[12:15]
	ds_read_b64_tr_b16 v[20:21], v159 offset:26312
	ds_read_b64_tr_b16 v[22:23], v159 offset:27400
	s_waitcnt lgkmcnt(0)
	v_mfma_f32_16x16x32_bf16 v[12:15], v[20:23], v[44:47], v[12:15]
	s_nop 7
	v_add_f32_e32 v5, v56, v12
	v_mul_f32_e32 v4, v5, v4
	v_lshlrev_b32_e32 v5, 16, v2
	v_mul_f32_e32 v4, v4, v5
	v_and_b32_e32 v5, 0xffff0000, v6
	v_add_f32_e32 v6, v56, v13
	v_mul_f32_e32 v5, v6, v5
	v_and_b32_e32 v2, 0xffff0000, v2
	v_mul_f32_e32 v2, v5, v2
	v_lshlrev_b32_e32 v5, 16, v7
	v_add_f32_e32 v6, v56, v14
	v_mul_f32_e32 v5, v6, v5
	v_lshlrev_b32_e32 v6, 16, v3
	v_mul_f32_e32 v5, v5, v6
	v_and_b32_e32 v6, 0xffff0000, v7
	v_add_f32_e32 v7, v56, v15
	v_mul_f32_e32 v6, v7, v6
	v_and_b32_e32 v3, 0xffff0000, v3
	v_mul_f32_e32 v3, v6, v3
	v_cvt_pk_bf16_f32 v2, v4, v2
	v_cvt_pk_bf16_f32 v3, v5, v3
	global_store_dwordx4 v[148:149], v[24:27], off offset:768
	global_store_dwordx4 v[148:149], v[16:19], off offset:832
	global_store_dwordx4 v[148:149], v[8:11], off offset:896
	global_store_dwordx4 v[148:149], v[0:3], off offset:960
	s_cbranch_scc1 .LBB0_421
.LBB0_422:
	s_ashr_i32 s84, s9, 8
	s_ashr_i32 s85, s2, 2
	s_and_b32 s85, s85, -2
	s_add_i32 s84, s84, s85
	s_bfe_u32 s85, s9, 0x20006
	s_lshl_b32 s85, s85, 4
	v_or_b32_e32 v192, s85, v150
	v_readlane_b32 s60, v252, 2
	v_readlane_b32 s61, v252, 3
	s_nop 3
	s_and_b32 s62, s2, 7
	s_lshl_b32 s62, s62, 7
	s_add_u32 s60, s60, s62
	s_addc_u32 s61, s61, 0
	v_and_b32_e32 v194, 24, v152
	v_lshlrev_b32_e32 v194, 1, v194
	v_mov_b32_e32 v195, 0
	v_lshl_add_u64 v[194:195], s[60:61], 0, v[194:195]
	s_ashr_i32 s85, s84, 4
	s_mul_hi_i32 s89, s85, 0x1100
	s_mul_i32 s88, s85, 0x1100
	s_lshl_b32 s90, s84, 2
	s_and_b32 s90, s90, 60
	s_lshl_b32 s90, s90, 6
	s_mov_b32 s87, 0
	v_or_b32_e32 v188, s88, v192
	v_mov_b32_e32 v189, s89
	s_mov_b32 s86, s90
	v_lshl_add_u64 v[190:191], v[188:189], 0, s[86:87]
	v_lshlrev_b64 v[190:191], 10, v[190:191]
	v_lshl_add_u64 v[190:191], v[194:195], 0, v[190:191]
	global_load_dwordx4 v[132:135], v[190:191], off
	global_load_dwordx4 v[136:139], v[190:191], off offset:64
	s_or_b32 s86, s90, 0x40
	v_lshl_add_u64 v[190:191], v[188:189], 0, s[86:87]
	v_lshlrev_b64 v[190:191], 10, v[190:191]
	v_lshl_add_u64 v[190:191], v[194:195], 0, v[190:191]
	global_load_dwordx4 v[140:143], v[190:191], off
	global_load_dwordx4 v[144:147], v[190:191], off offset:64
	s_or_b32 s86, s90, 0x80
	v_lshl_add_u64 v[190:191], v[188:189], 0, s[86:87]
	v_lshlrev_b64 v[190:191], 10, v[190:191]
	v_lshl_add_u64 v[190:191], v[194:195], 0, v[190:191]
	global_load_dwordx4 v[196:199], v[190:191], off
	global_load_dwordx4 v[200:203], v[190:191], off offset:64
	s_or_b32 s86, s90, 0xc0
	v_lshl_add_u64 v[190:191], v[188:189], 0, s[86:87]
	v_lshlrev_b64 v[190:191], 10, v[190:191]
	v_lshl_add_u64 v[190:191], v[194:195], 0, v[190:191]
	global_load_dwordx4 v[156:159], v[190:191], off
	global_load_dwordx4 v[160:163], v[190:191], off offset:64
	v_lshlrev_b32_e32 v204, 2, v226
	global_load_dword v255, v204, s[24:25]
	v_lshlrev_b32_e32 v204, 2, v96
	global_load_dword v205, v204, s[26:27]
	v_add_u32_e32 v204, 0x200, v96
	v_min_i32_e32 v204, 0xe87, v204
	v_lshlrev_b32_e32 v204, 2, v204
	global_load_dword v206, v204, s[26:27]
	v_add_u32_e32 v204, 0x400, v96
	v_min_i32_e32 v204, 0xe87, v204
	v_lshlrev_b32_e32 v204, 2, v204
	global_load_dword v207, v204, s[26:27]
	v_add_u32_e32 v204, 0x600, v96
	v_min_i32_e32 v204, 0xe87, v204
	v_lshlrev_b32_e32 v204, 2, v204
	global_load_dword v208, v204, s[26:27]
	v_add_u32_e32 v204, 0x800, v96
	v_min_i32_e32 v204, 0xe87, v204
	v_lshlrev_b32_e32 v204, 2, v204
	global_load_dword v209, v204, s[26:27]
	v_add_u32_e32 v204, 0xa00, v96
	v_min_i32_e32 v204, 0xe87, v204
	v_lshlrev_b32_e32 v204, 2, v204
	global_load_dword v210, v204, s[26:27]
	v_add_u32_e32 v204, 0xc00, v96
	v_min_i32_e32 v204, 0xe87, v204
	v_lshlrev_b32_e32 v204, 2, v204
	global_load_dword v211, v204, s[26:27]
	v_add_u32_e32 v204, 0xe00, v96
	v_min_i32_e32 v204, 0xe87, v204
	v_lshlrev_b32_e32 v204, 2, v204
	global_load_dword v212, v204, s[26:27]
	v_cmp_eq_u32_e32 vcc, 0, v96
	s_waitcnt lgkmcnt(0)
	s_barrier
	s_and_saveexec_b64 s[0:1], vcc
	v_mov_b32_e32 v0, 0
	ds_write_b32 v0, v0 offset:30720
	s_or_b64 exec, exec, s[0:1]
	s_movk_i32 s0, 0x1e00
	v_cmp_gt_i32_e32 vcc, s0, v96
	s_waitcnt lgkmcnt(0)
	s_barrier
	s_and_saveexec_b64 s[0:1], vcc
	s_cbranch_execz .LBB0_427
	v_add_u32_e32 v0, 0xfffffe00, v96
	v_lshl_add_u32 v1, v96, 2, 0
	s_mov_b64 s[6:7], 0
	v_mov_b32_e32 v2, 0
	s_movk_i32 s4, 0x1bff

.LBB0_427:
	s_or_b64 exec, exec, s[0:1]
	v_add_u32_e32 v13, 0x200, v96
	v_min_i32_e32 v0, 0xe87, v13
	v_ashrrev_i32_e32 v1, 31, v0
	v_add_u32_e32 v11, 0x400, v96
	v_lshl_add_u64 v[2:3], v[0:1], 2, s[26:27]
	v_min_i32_e32 v0, 0xe87, v11
	v_ashrrev_i32_e32 v1, 31, v0
	v_add_u32_e32 v9, 0x600, v96
	v_lshl_add_u64 v[16:17], v[0:1], 2, s[26:27]
	v_min_i32_e32 v0, 0xe87, v9
	v_ashrrev_i32_e32 v1, 31, v0
	v_add_u32_e32 v7, 0x800, v96
	v_lshl_add_u64 v[18:19], v[0:1], 2, s[26:27]
	v_min_i32_e32 v0, 0xe87, v7
	v_ashrrev_i32_e32 v1, 31, v0
	v_add_u32_e32 v6, 0xa00, v96
	v_lshl_add_u64 v[20:21], v[0:1], 2, s[26:27]
	v_min_i32_e32 v0, 0xe87, v6
	v_ashrrev_i32_e32 v1, 31, v0
	v_add_u32_e32 v4, 0xc00, v96
	v_lshl_add_u64 v[22:23], v[0:1], 2, s[26:27]
	v_min_i32_e32 v0, 0xe87, v4
	v_ashrrev_i32_e32 v1, 31, v0
	v_lshl_add_u64 v[24:25], v[0:1], 2, s[26:27]
	v_add_u32_e32 v0, 0xe00, v96
	v_min_i32_e32 v14, 0xe87, v0
	v_ashrrev_i32_e32 v15, 31, v14
	s_waitcnt lgkmcnt(0)
	s_barrier
	v_lshl_add_u64 v[26:27], v[14:15], 2, s[26:27]
	v_mov_b32_e32 v15, v206
	v_mov_b32_e32 v14, v207
	v_mov_b32_e32 v12, v208
	v_mov_b32_e32 v10, v209
	v_mov_b32_e32 v8, v210
	v_mov_b32_e32 v5, v211
	v_mov_b32_e32 v1, v212
	s_movk_i32 s0, 0xe88
	v_cmp_gt_i32_e32 vcc, s0, v96
	v_mov_b32_e32 v2, 0
	v_lshlrev_b32_e32 v3, 2, v96
	s_and_saveexec_b64 s[0:1], vcc
	s_cbranch_execz .LBB0_429
	v_lshl_add_u64 v[16:17], v[96:97], 2, s[26:27]
	v_mov_b32_e32 v2, v205
	s_mov_b32 s4, 0x84210843
	v_mul_hi_i32 v16, v96, s4
	v_add_u32_e32 v16, v16, v96
	v_lshrrev_b32_e32 v17, 31, v16
	v_ashrrev_i32_e32 v16, 4, v16
	s_movk_i32 s5, 0xff84
	v_add_u32_e32 v16, v16, v17
	v_lshl_add_u32 v17, v16, 8, 0
	v_mul_lo_u32 v16, v16, s5
	v_add3_u32 v16, v17, v16, v3
	s_waitcnt vmcnt(0)
	v_mul_f32_e32 v2, 0x3fb8aa3b, v2
	ds_write_b32 v16, v2 offset:64
	v_max_f32_e64 v2, |v2|, 0
